# bf16 accumulate chains alternate k order (k0,k1 then k1,k0) so chain-boundary MFMAs share the same srcA register; per-accumulator summation order of the two k-steps swaps on odd chains
# baseline (speedup 1.0000x reference)
.LBB0_170:
	ds_read_b128 v[128:131], v168
	ds_read_b128 v[132:135], v168 offset:1024
	ds_read_b128 v[136:139], v168 offset:2048
	ds_read_b128 v[140:143], v168 offset:3072
	ds_read_b128 v[152:155], v169
	ds_read_b128 v[156:159], v169 offset:1024
	ds_read_b128 v[160:163], v169 offset:2048
	ds_read_b128 v[172:175], v169 offset:3072
	s_add_u32 s2, s52, 0x10000
	s_addc_u32 s3, s53, 0
	s_cmp_eq_u32 s88, 60
	s_cselect_b32 s48, s82, s2
	s_cselect_b32 s49, s39, s3
	s_cselect_b32 s90, s83, s54
	s_cselect_b32 s91, s15, s55
	s_add_u32 s80, s48, 0x8000
	s_addc_u32 s81, s49, 0
	ds_read_b128 v[176:179], v170
	ds_read_b128 v[180:183], v170 offset:1024
	ds_read_b128 v[184:187], v170 offset:2048
	ds_read_b128 v[188:191], v170 offset:3072
	ds_read_b128 v[192:195], v170 offset:4096
	ds_read_b128 v[196:199], v170 offset:5120
	ds_read_b128 v[200:203], v170 offset:6144
	ds_read_b128 v[204:207], v170 offset:7168
	s_add_u32 s92, s52, 0xc000
	s_addc_u32 s93, s53, 0
	s_mov_b32 m0, s72
	s_nop 0
	global_load_lds_dwordx4 v166, s[92:93]
	s_add_u32 s52, s52, 0xe000
	s_addc_u32 s53, s53, 0
	s_mov_b32 m0, s75
	s_nop 0
	global_load_lds_dwordx4 v166, s[52:53]
	s_waitcnt vmcnt(8)
	s_waitcnt lgkmcnt(0)
	s_add_u32 s92, s90, 0x8000
	s_addc_u32 s93, s91, 0
	s_barrier
	s_setprio 1
	s_waitcnt lgkmcnt(7)
	s_waitcnt lgkmcnt(0)
	v_mfma_f32_16x16x32_bf16 v[112:115], v[128:131], v[176:179], v[112:115]
	v_mfma_f32_16x16x32_bf16 v[112:115], v[132:135], v[180:183], v[112:115]
	v_mfma_f32_16x16x32_bf16 v[96:99], v[132:135], v[188:191], v[96:99]
	v_mfma_f32_16x16x32_bf16 v[96:99], v[128:131], v[184:187], v[96:99]
	v_mfma_f32_16x16x32_bf16 v[80:83], v[128:131], v[192:195], v[80:83]
	v_mfma_f32_16x16x32_bf16 v[80:83], v[132:135], v[196:199], v[80:83]
	v_mfma_f32_16x16x32_bf16 v[60:63], v[132:135], v[204:207], v[60:63]
	v_mfma_f32_16x16x32_bf16 v[60:63], v[128:131], v[200:203], v[60:63]
	v_mfma_f32_16x16x32_bf16 v[72:75], v[136:139], v[200:203], v[72:75]
	v_mfma_f32_16x16x32_bf16 v[72:75], v[140:143], v[204:207], v[72:75]
	v_mfma_f32_16x16x32_bf16 v[88:91], v[140:143], v[196:199], v[88:91]
	v_mfma_f32_16x16x32_bf16 v[88:91], v[136:139], v[192:195], v[88:91]
	v_mfma_f32_16x16x32_bf16 v[104:107], v[136:139], v[184:187], v[104:107]
	v_mfma_f32_16x16x32_bf16 v[104:107], v[140:143], v[188:191], v[104:107]
	v_mfma_f32_16x16x32_bf16 v[120:123], v[140:143], v[180:183], v[120:123]
	v_mfma_f32_16x16x32_bf16 v[120:123], v[136:139], v[176:179], v[120:123]
	s_setprio 0
	s_setprio 1
	s_waitcnt lgkmcnt(0)
	v_mfma_f32_16x16x32_bf16 v[116:119], v[152:155], v[176:179], v[116:119]
	v_mfma_f32_16x16x32_bf16 v[116:119], v[156:159], v[180:183], v[116:119]
	v_mfma_f32_16x16x32_bf16 v[100:103], v[156:159], v[188:191], v[100:103]
	v_mfma_f32_16x16x32_bf16 v[100:103], v[152:155], v[184:187], v[100:103]
	v_mfma_f32_16x16x32_bf16 v[84:87], v[152:155], v[192:195], v[84:87]
	v_mfma_f32_16x16x32_bf16 v[84:87], v[156:159], v[196:199], v[84:87]
	v_mfma_f32_16x16x32_bf16 v[68:71], v[156:159], v[204:207], v[68:71]
	v_mfma_f32_16x16x32_bf16 v[68:71], v[152:155], v[200:203], v[68:71]
	v_mfma_f32_16x16x32_bf16 v[76:79], v[160:163], v[200:203], v[76:79]
	v_mfma_f32_16x16x32_bf16 v[76:79], v[172:175], v[204:207], v[76:79]
	v_mfma_f32_16x16x32_bf16 v[92:95], v[172:175], v[196:199], v[92:95]
	v_mfma_f32_16x16x32_bf16 v[92:95], v[160:163], v[192:195], v[92:95]
	v_mfma_f32_16x16x32_bf16 v[108:111], v[160:163], v[184:187], v[108:111]
	v_mfma_f32_16x16x32_bf16 v[108:111], v[172:175], v[188:191], v[108:111]
	v_mfma_f32_16x16x32_bf16 v[124:127], v[172:175], v[180:183], v[124:127]
	v_mfma_f32_16x16x32_bf16 v[124:127], v[160:163], v[176:179], v[124:127]
	s_setprio 0
	s_barrier
	s_add_u32 s52, s90, 0x2000
	ds_read_b128 v[176:179], v170 offset:16384
	ds_read_b128 v[180:183], v170 offset:17408
	ds_read_b128 v[184:187], v170 offset:18432
	ds_read_b128 v[188:191], v170 offset:19456
	ds_read_b128 v[192:195], v170 offset:20480
	ds_read_b128 v[196:199], v170 offset:21504
	ds_read_b128 v[200:203], v170 offset:22528
	ds_read_b128 v[204:207], v170 offset:23552
	s_mov_b32 m0, s45
	s_nop 0
	global_load_lds_dwordx4 v166, s[90:91]
	s_addc_u32 s53, s91, 0
	s_mov_b32 m0, s47
	s_nop 0
	global_load_lds_dwordx4 v166, s[52:53]
	s_add_u32 s52, s90, 0x4000
	s_addc_u32 s53, s91, 0
	s_mov_b32 m0, s58
	s_nop 0
	global_load_lds_dwordx4 v166, s[52:53]
	s_add_u32 s52, s90, 0x6000
	s_addc_u32 s53, s91, 0
	s_mov_b32 m0, s59
	s_nop 0
	global_load_lds_dwordx4 v166, s[52:53]
	s_add_u32 s52, s48, 0x2000
	s_mov_b32 m0, s57
	s_nop 0
	global_load_lds_dwordx4 v166, s[48:49]
	s_addc_u32 s53, s49, 0
	s_mov_b32 m0, s60
	s_nop 0
	global_load_lds_dwordx4 v166, s[52:53]
	s_waitcnt vmcnt(8)
	s_waitcnt lgkmcnt(0)
	s_barrier
	s_setprio 1
	s_waitcnt lgkmcnt(7)
	s_waitcnt lgkmcnt(0)
	v_mfma_f32_16x16x32_bf16 v[48:51], v[128:131], v[176:179], v[48:51]
	v_mfma_f32_16x16x32_bf16 v[48:51], v[132:135], v[180:183], v[48:51]
	v_mfma_f32_16x16x32_bf16 v[32:35], v[132:135], v[188:191], v[32:35]
	v_mfma_f32_16x16x32_bf16 v[32:35], v[128:131], v[184:187], v[32:35]
	v_mfma_f32_16x16x32_bf16 v[16:19], v[128:131], v[192:195], v[16:19]
	v_mfma_f32_16x16x32_bf16 v[16:19], v[132:135], v[196:199], v[16:19]
	v_mfma_f32_16x16x32_bf16 v[0:3], v[132:135], v[204:207], v[0:3]
	v_mfma_f32_16x16x32_bf16 v[0:3], v[128:131], v[200:203], v[0:3]
	v_mfma_f32_16x16x32_bf16 v[8:11], v[136:139], v[200:203], v[8:11]
	v_mfma_f32_16x16x32_bf16 v[8:11], v[140:143], v[204:207], v[8:11]
	v_mfma_f32_16x16x32_bf16 v[24:27], v[140:143], v[196:199], v[24:27]
	v_mfma_f32_16x16x32_bf16 v[24:27], v[136:139], v[192:195], v[24:27]
	v_mfma_f32_16x16x32_bf16 v[40:43], v[136:139], v[184:187], v[40:43]
	v_mfma_f32_16x16x32_bf16 v[40:43], v[140:143], v[188:191], v[40:43]
	v_mfma_f32_16x16x32_bf16 v[56:59], v[140:143], v[180:183], v[56:59]
	v_mfma_f32_16x16x32_bf16 v[56:59], v[136:139], v[176:179], v[56:59]
	s_setprio 0
	s_setprio 1
	s_waitcnt lgkmcnt(0)
	v_mfma_f32_16x16x32_bf16 v[52:55], v[152:155], v[176:179], v[52:55]
	v_mfma_f32_16x16x32_bf16 v[52:55], v[156:159], v[180:183], v[52:55]
	v_mfma_f32_16x16x32_bf16 v[36:39], v[156:159], v[188:191], v[36:39]
	v_mfma_f32_16x16x32_bf16 v[36:39], v[152:155], v[184:187], v[36:39]
	v_mfma_f32_16x16x32_bf16 v[20:23], v[152:155], v[192:195], v[20:23]
	v_mfma_f32_16x16x32_bf16 v[20:23], v[156:159], v[196:199], v[20:23]
	v_mfma_f32_16x16x32_bf16 v[4:7], v[156:159], v[204:207], v[4:7]
	v_mfma_f32_16x16x32_bf16 v[4:7], v[152:155], v[200:203], v[4:7]
	v_mfma_f32_16x16x32_bf16 v[12:15], v[160:163], v[200:203], v[12:15]
	v_mfma_f32_16x16x32_bf16 v[12:15], v[172:175], v[204:207], v[12:15]
	v_mfma_f32_16x16x32_bf16 v[28:31], v[172:175], v[196:199], v[28:31]
	v_mfma_f32_16x16x32_bf16 v[28:31], v[160:163], v[192:195], v[28:31]
	v_mfma_f32_16x16x32_bf16 v[44:47], v[160:163], v[184:187], v[44:47]
	v_mfma_f32_16x16x32_bf16 v[44:47], v[172:175], v[188:191], v[44:47]
	v_mfma_f32_16x16x32_bf16 v[64:67], v[172:175], v[180:183], v[64:67]
	v_mfma_f32_16x16x32_bf16 v[64:67], v[160:163], v[176:179], v[64:67]
	s_setprio 0
	s_barrier
	ds_read_b128 v[128:131], v148
	ds_read_b128 v[132:135], v148 offset:1024
	ds_read_b128 v[136:139], v148 offset:2048
	ds_read_b128 v[140:143], v148 offset:3072
	ds_read_b128 v[152:155], v150
	ds_read_b128 v[156:159], v150 offset:1024
	ds_read_b128 v[160:163], v150 offset:2048
	ds_read_b128 v[172:175], v150 offset:3072
	ds_read_b128 v[176:179], v170 offset:32768
	ds_read_b128 v[180:183], v170 offset:33792
	ds_read_b128 v[184:187], v170 offset:34816
	ds_read_b128 v[188:191], v170 offset:35840
	ds_read_b128 v[192:195], v170 offset:36864
	ds_read_b128 v[196:199], v170 offset:37888
	ds_read_b128 v[200:203], v170 offset:38912
	ds_read_b128 v[204:207], v170 offset:39936
	s_add_u32 s52, s48, 0x4000
	s_addc_u32 s53, s49, 0
	s_mov_b32 m0, s61
	s_nop 0
	global_load_lds_dwordx4 v166, s[52:53]
	s_add_u32 s52, s48, 0x6000
	s_addc_u32 s53, s49, 0
	s_mov_b32 m0, s62
	s_nop 0
	global_load_lds_dwordx4 v166, s[52:53]
	s_waitcnt vmcnt(8)
	s_waitcnt lgkmcnt(0)
	s_barrier
	s_setprio 1
	s_waitcnt lgkmcnt(7)
	s_waitcnt lgkmcnt(0)
	v_mfma_f32_16x16x32_bf16 v[112:115], v[128:131], v[176:179], v[112:115]
	v_mfma_f32_16x16x32_bf16 v[112:115], v[132:135], v[180:183], v[112:115]
	v_mfma_f32_16x16x32_bf16 v[96:99], v[132:135], v[188:191], v[96:99]
	v_mfma_f32_16x16x32_bf16 v[96:99], v[128:131], v[184:187], v[96:99]
	v_mfma_f32_16x16x32_bf16 v[80:83], v[128:131], v[192:195], v[80:83]
	v_mfma_f32_16x16x32_bf16 v[80:83], v[132:135], v[196:199], v[80:83]
	v_mfma_f32_16x16x32_bf16 v[60:63], v[132:135], v[204:207], v[60:63]
	v_mfma_f32_16x16x32_bf16 v[60:63], v[128:131], v[200:203], v[60:63]
	v_mfma_f32_16x16x32_bf16 v[72:75], v[136:139], v[200:203], v[72:75]
	v_mfma_f32_16x16x32_bf16 v[72:75], v[140:143], v[204:207], v[72:75]
	v_mfma_f32_16x16x32_bf16 v[88:91], v[140:143], v[196:199], v[88:91]
	v_mfma_f32_16x16x32_bf16 v[88:91], v[136:139], v[192:195], v[88:91]
	v_mfma_f32_16x16x32_bf16 v[104:107], v[136:139], v[184:187], v[104:107]
	v_mfma_f32_16x16x32_bf16 v[104:107], v[140:143], v[188:191], v[104:107]
	v_mfma_f32_16x16x32_bf16 v[120:123], v[140:143], v[180:183], v[120:123]
	v_mfma_f32_16x16x32_bf16 v[120:123], v[136:139], v[176:179], v[120:123]
	s_setprio 0
	s_setprio 1
	s_waitcnt lgkmcnt(0)
	v_mfma_f32_16x16x32_bf16 v[116:119], v[152:155], v[176:179], v[116:119]
	v_mfma_f32_16x16x32_bf16 v[116:119], v[156:159], v[180:183], v[116:119]
	v_mfma_f32_16x16x32_bf16 v[100:103], v[156:159], v[188:191], v[100:103]
	v_mfma_f32_16x16x32_bf16 v[100:103], v[152:155], v[184:187], v[100:103]
	v_mfma_f32_16x16x32_bf16 v[84:87], v[152:155], v[192:195], v[84:87]
	v_mfma_f32_16x16x32_bf16 v[84:87], v[156:159], v[196:199], v[84:87]
	v_mfma_f32_16x16x32_bf16 v[68:71], v[156:159], v[204:207], v[68:71]
	v_mfma_f32_16x16x32_bf16 v[68:71], v[152:155], v[200:203], v[68:71]
	v_mfma_f32_16x16x32_bf16 v[76:79], v[160:163], v[200:203], v[76:79]
	v_mfma_f32_16x16x32_bf16 v[76:79], v[172:175], v[204:207], v[76:79]
	v_mfma_f32_16x16x32_bf16 v[92:95], v[172:175], v[196:199], v[92:95]
	v_mfma_f32_16x16x32_bf16 v[92:95], v[160:163], v[192:195], v[92:95]
	v_mfma_f32_16x16x32_bf16 v[108:111], v[160:163], v[184:187], v[108:111]
	v_mfma_f32_16x16x32_bf16 v[108:111], v[172:175], v[188:191], v[108:111]
	v_mfma_f32_16x16x32_bf16 v[124:127], v[172:175], v[180:183], v[124:127]
	v_mfma_f32_16x16x32_bf16 v[124:127], v[160:163], v[176:179], v[124:127]
	s_setprio 0
	s_barrier
	s_add_u32 s52, s90, 0xa000
	ds_read_b128 v[176:179], v170 offset:49152
	ds_read_b128 v[180:183], v170 offset:50176
	ds_read_b128 v[184:187], v170 offset:51200
	ds_read_b128 v[188:191], v170 offset:52224
	ds_read_b128 v[192:195], v170 offset:53248
	ds_read_b128 v[196:199], v170 offset:54272
	ds_read_b128 v[200:203], v170 offset:55296
	ds_read_b128 v[204:207], v170 offset:56320
	s_mov_b32 m0, s66
	s_nop 0
	global_load_lds_dwordx4 v166, s[92:93]
	s_addc_u32 s53, s91, 0
	s_mov_b32 m0, s67
	s_nop 0
	global_load_lds_dwordx4 v166, s[52:53]
	s_add_u32 s52, s90, 0xc000
	s_addc_u32 s53, s91, 0
	s_mov_b32 m0, s70
	s_nop 0
	global_load_lds_dwordx4 v166, s[52:53]
	s_add_u32 s52, s90, 0xe000
	s_addc_u32 s53, s91, 0
	s_mov_b32 m0, s71
	s_nop 0
	global_load_lds_dwordx4 v166, s[52:53]
	s_add_u32 s48, s48, 0xa000
	s_mov_b32 m0, s68
	s_nop 0
	global_load_lds_dwordx4 v166, s[80:81]
	s_addc_u32 s49, s49, 0
	s_mov_b32 m0, s69
	s_nop 0
	global_load_lds_dwordx4 v166, s[48:49]
	s_waitcnt vmcnt(8)
	s_waitcnt lgkmcnt(0)
	s_barrier
	s_setprio 1
	s_waitcnt lgkmcnt(7)
	s_waitcnt lgkmcnt(0)
	v_mfma_f32_16x16x32_bf16 v[48:51], v[128:131], v[176:179], v[48:51]
	v_mfma_f32_16x16x32_bf16 v[48:51], v[132:135], v[180:183], v[48:51]
	v_mfma_f32_16x16x32_bf16 v[32:35], v[132:135], v[188:191], v[32:35]
	v_mfma_f32_16x16x32_bf16 v[32:35], v[128:131], v[184:187], v[32:35]
	v_mfma_f32_16x16x32_bf16 v[16:19], v[128:131], v[192:195], v[16:19]
	v_mfma_f32_16x16x32_bf16 v[16:19], v[132:135], v[196:199], v[16:19]
	v_mfma_f32_16x16x32_bf16 v[0:3], v[132:135], v[204:207], v[0:3]
	v_mfma_f32_16x16x32_bf16 v[0:3], v[128:131], v[200:203], v[0:3]
	v_mfma_f32_16x16x32_bf16 v[8:11], v[136:139], v[200:203], v[8:11]
	v_mfma_f32_16x16x32_bf16 v[8:11], v[140:143], v[204:207], v[8:11]
	v_mfma_f32_16x16x32_bf16 v[24:27], v[140:143], v[196:199], v[24:27]
	v_mfma_f32_16x16x32_bf16 v[24:27], v[136:139], v[192:195], v[24:27]
	v_mfma_f32_16x16x32_bf16 v[40:43], v[136:139], v[184:187], v[40:43]
	v_mfma_f32_16x16x32_bf16 v[40:43], v[140:143], v[188:191], v[40:43]
	v_mfma_f32_16x16x32_bf16 v[56:59], v[140:143], v[180:183], v[56:59]
	v_mfma_f32_16x16x32_bf16 v[56:59], v[136:139], v[176:179], v[56:59]
	s_setprio 0
	s_setprio 1
	s_waitcnt lgkmcnt(0)
	v_mfma_f32_16x16x32_bf16 v[52:55], v[152:155], v[176:179], v[52:55]
	v_mfma_f32_16x16x32_bf16 v[52:55], v[156:159], v[180:183], v[52:55]
	v_mfma_f32_16x16x32_bf16 v[36:39], v[156:159], v[188:191], v[36:39]
	v_mfma_f32_16x16x32_bf16 v[36:39], v[152:155], v[184:187], v[36:39]
	v_mfma_f32_16x16x32_bf16 v[20:23], v[152:155], v[192:195], v[20:23]
	v_mfma_f32_16x16x32_bf16 v[20:23], v[156:159], v[196:199], v[20:23]
	v_mfma_f32_16x16x32_bf16 v[4:7], v[156:159], v[204:207], v[4:7]
	v_mfma_f32_16x16x32_bf16 v[4:7], v[152:155], v[200:203], v[4:7]
	v_mfma_f32_16x16x32_bf16 v[12:15], v[160:163], v[200:203], v[12:15]
	v_mfma_f32_16x16x32_bf16 v[12:15], v[172:175], v[204:207], v[12:15]
	v_mfma_f32_16x16x32_bf16 v[28:31], v[172:175], v[196:199], v[28:31]
	v_mfma_f32_16x16x32_bf16 v[28:31], v[160:163], v[192:195], v[28:31]
	v_mfma_f32_16x16x32_bf16 v[44:47], v[160:163], v[184:187], v[44:47]
	v_mfma_f32_16x16x32_bf16 v[44:47], v[172:175], v[188:191], v[44:47]
	v_mfma_f32_16x16x32_bf16 v[64:67], v[172:175], v[180:183], v[64:67]
	v_mfma_f32_16x16x32_bf16 v[64:67], v[160:163], v[176:179], v[64:67]
	s_setprio 0
	s_barrier
	s_add_i32 s88, s88, 2
	s_add_u32 s54, s54, 0x10000
	s_addc_u32 s55, s55, 0
	s_cmp_gt_u32 s88, 61
	s_mov_b64 s[52:53], s[2:3]
	s_cbranch_scc0 .LBB0_170
	s_and_b64 vcc, exec, s[12:13]
	s_cbranch_vccz .LBB0_173
	s_barrier

.LBB0_326:
	ds_read_b128 v[60:63], v212
	ds_read_b128 v[68:71], v212 offset:1024
	ds_read_b128 v[88:91], v212 offset:2048
	ds_read_b128 v[92:95], v212 offset:3072
	ds_read_b128 v[112:115], v213
	ds_read_b128 v[116:119], v213 offset:1024
	ds_read_b128 v[138:141], v213 offset:2048
	ds_read_b128 v[152:155], v213 offset:3072
	s_cmpk_eq_i32 s80, 0xa8
	s_cselect_b32 s2, s4, s76
	s_cselect_b32 s3, s5, s77
	s_cselect_b32 s42, s38, s78
	s_cselect_b32 s43, s39, s79
	s_add_u32 s40, s2, 0x8000
	s_addc_u32 s41, s3, 0
	ds_read_b128 v[164:167], v214
	ds_read_b128 v[168:171], v214 offset:1024
	ds_read_b128 v[172:175], v214 offset:2048
	ds_read_b128 v[176:179], v214 offset:3072
	ds_read_b128 v[180:183], v214 offset:4096
	ds_read_b128 v[184:187], v214 offset:5120
	ds_read_b128 v[188:191], v214 offset:6144
	ds_read_b128 v[192:195], v214 offset:7168
	s_add_u32 s44, s76, 0xffffc000
	s_addc_u32 s45, s77, -1
	s_mov_b32 m0, s65
	s_nop 0
	global_load_lds_dwordx4 v210, s[44:45]
	s_add_u32 s44, s76, 0xffffe000
	s_addc_u32 s45, s77, -1
	s_mov_b32 m0, s68
	s_nop 0
	global_load_lds_dwordx4 v210, s[44:45]
	s_waitcnt vmcnt(8)
	s_waitcnt lgkmcnt(0)
	s_add_u32 s44, s42, 0x8000
	s_addc_u32 s45, s43, 0
	s_barrier
	s_setprio 1
	s_waitcnt lgkmcnt(7)
	s_waitcnt lgkmcnt(0)
	v_mfma_f32_16x16x32_bf16 v[160:163], v[60:63], v[164:167], v[160:163]
	v_mfma_f32_16x16x32_bf16 v[160:163], v[68:71], v[168:171], v[160:163]
	v_mfma_f32_16x16x32_bf16 v[132:135], v[68:71], v[176:179], v[132:135]
	v_mfma_f32_16x16x32_bf16 v[132:135], v[60:63], v[172:175], v[132:135]
	v_mfma_f32_16x16x32_bf16 v[108:111], v[60:63], v[180:183], v[108:111]
	v_mfma_f32_16x16x32_bf16 v[108:111], v[68:71], v[184:187], v[108:111]
	v_mfma_f32_16x16x32_bf16 v[84:87], v[68:71], v[192:195], v[84:87]
	v_mfma_f32_16x16x32_bf16 v[84:87], v[60:63], v[188:191], v[84:87]
	v_mfma_f32_16x16x32_bf16 v[80:83], v[88:91], v[188:191], v[80:83]
	v_mfma_f32_16x16x32_bf16 v[80:83], v[92:95], v[192:195], v[80:83]
	v_mfma_f32_16x16x32_bf16 v[104:107], v[92:95], v[184:187], v[104:107]
	v_mfma_f32_16x16x32_bf16 v[104:107], v[88:91], v[180:183], v[104:107]
	v_mfma_f32_16x16x32_bf16 v[128:131], v[88:91], v[172:175], v[128:131]
	v_mfma_f32_16x16x32_bf16 v[128:131], v[92:95], v[176:179], v[128:131]
	v_mfma_f32_16x16x32_bf16 v[156:159], v[92:95], v[168:171], v[156:159]
	v_mfma_f32_16x16x32_bf16 v[156:159], v[88:91], v[164:167], v[156:159]
	s_setprio 0
	s_setprio 1
	v_mfma_f32_16x16x32_bf16 v[148:151], v[112:115], v[164:167], v[148:151]
	v_mfma_f32_16x16x32_bf16 v[142:145], v[138:141], v[164:167], v[144:147]
	v_mfma_f32_16x16x32_bf16 v[124:127], v[112:115], v[172:175], v[124:127]
	v_mfma_f32_16x16x32_bf16 v[120:123], v[138:141], v[172:175], v[120:123]
	v_mfma_f32_16x16x32_bf16 v[100:103], v[112:115], v[180:183], v[100:103]
	v_mfma_f32_16x16x32_bf16 v[96:99], v[138:141], v[180:183], v[96:99]
	v_mfma_f32_16x16x32_bf16 v[76:79], v[112:115], v[188:191], v[76:79]
	v_mfma_f32_16x16x32_bf16 v[72:75], v[138:141], v[188:191], v[72:75]
	v_mfma_f32_16x16x32_bf16 v[148:151], v[116:119], v[168:171], v[148:151]
	v_mfma_f32_16x16x32_bf16 v[142:145], v[152:155], v[168:171], v[142:145]
	v_mfma_f32_16x16x32_bf16 v[124:127], v[116:119], v[176:179], v[124:127]
	v_mfma_f32_16x16x32_bf16 v[120:123], v[152:155], v[176:179], v[120:123]
	v_mfma_f32_16x16x32_bf16 v[100:103], v[116:119], v[184:187], v[100:103]
	v_mfma_f32_16x16x32_bf16 v[96:99], v[152:155], v[184:187], v[96:99]
	v_mfma_f32_16x16x32_bf16 v[76:79], v[116:119], v[192:195], v[76:79]
	v_mfma_f32_16x16x32_bf16 v[72:75], v[152:155], v[192:195], v[72:75]
	s_setprio 0
	s_barrier
	s_add_u32 s82, s42, 0x2000
	ds_read_b128 v[164:167], v214 offset:16384
	ds_read_b128 v[168:171], v214 offset:17408
	ds_read_b128 v[172:175], v214 offset:18432
	ds_read_b128 v[176:179], v214 offset:19456
	ds_read_b128 v[180:183], v214 offset:20480
	ds_read_b128 v[184:187], v214 offset:21504
	ds_read_b128 v[188:191], v214 offset:22528
	ds_read_b128 v[192:195], v214 offset:23552
	s_mov_b32 m0, s47
	s_nop 0
	global_load_lds_dwordx4 v210, s[42:43]
	s_addc_u32 s83, s43, 0
	s_mov_b32 m0, s48
	s_nop 0
	global_load_lds_dwordx4 v210, s[82:83]
	s_add_u32 s82, s42, 0x4000
	s_addc_u32 s83, s43, 0
	s_mov_b32 m0, s49
	s_nop 0
	global_load_lds_dwordx4 v210, s[82:83]
	s_add_u32 s82, s42, 0x6000
	s_addc_u32 s83, s43, 0
	s_mov_b32 m0, s52
	s_nop 0
	global_load_lds_dwordx4 v210, s[82:83]
	s_add_u32 s82, s2, 0x2000
	s_mov_b32 m0, s46
	s_nop 0
	global_load_lds_dwordx4 v210, s[2:3]
	s_addc_u32 s83, s3, 0
	s_mov_b32 m0, s53
	s_nop 0
	global_load_lds_dwordx4 v210, s[82:83]
	s_waitcnt vmcnt(8)
	s_waitcnt lgkmcnt(0)
	s_barrier
	s_setprio 1
	s_waitcnt lgkmcnt(7)
	s_waitcnt lgkmcnt(0)
	v_mfma_f32_16x16x32_bf16 v[64:67], v[60:63], v[164:167], v[64:67]
	v_mfma_f32_16x16x32_bf16 v[64:67], v[68:71], v[168:171], v[64:67]
	v_mfma_f32_16x16x32_bf16 v[44:47], v[68:71], v[176:179], v[44:47]
	v_mfma_f32_16x16x32_bf16 v[44:47], v[60:63], v[172:175], v[44:47]
	v_mfma_f32_16x16x32_bf16 v[28:31], v[60:63], v[180:183], v[28:31]
	v_mfma_f32_16x16x32_bf16 v[28:31], v[68:71], v[184:187], v[28:31]
	v_mfma_f32_16x16x32_bf16 v[12:15], v[68:71], v[192:195], v[12:15]
	v_mfma_f32_16x16x32_bf16 v[12:15], v[60:63], v[188:191], v[12:15]
	v_mfma_f32_16x16x32_bf16 v[8:11], v[88:91], v[188:191], v[8:11]
	v_mfma_f32_16x16x32_bf16 v[8:11], v[92:95], v[192:195], v[8:11]
	v_mfma_f32_16x16x32_bf16 v[24:27], v[92:95], v[184:187], v[24:27]
	v_mfma_f32_16x16x32_bf16 v[24:27], v[88:91], v[180:183], v[24:27]
	v_mfma_f32_16x16x32_bf16 v[40:43], v[88:91], v[172:175], v[40:43]
	v_mfma_f32_16x16x32_bf16 v[40:43], v[92:95], v[176:179], v[40:43]
	v_mfma_f32_16x16x32_bf16 v[56:59], v[92:95], v[168:171], v[56:59]
	v_mfma_f32_16x16x32_bf16 v[56:59], v[88:91], v[164:167], v[56:59]
	s_setprio 0
	s_setprio 1
	s_waitcnt lgkmcnt(0)
	v_mfma_f32_16x16x32_bf16 v[52:55], v[112:115], v[164:167], v[52:55]
	v_mfma_f32_16x16x32_bf16 v[52:55], v[116:119], v[168:171], v[52:55]
	v_mfma_f32_16x16x32_bf16 v[36:39], v[116:119], v[176:179], v[36:39]
	v_mfma_f32_16x16x32_bf16 v[36:39], v[112:115], v[172:175], v[36:39]
	v_mfma_f32_16x16x32_bf16 v[20:23], v[112:115], v[180:183], v[20:23]
	v_mfma_f32_16x16x32_bf16 v[20:23], v[116:119], v[184:187], v[20:23]
	v_mfma_f32_16x16x32_bf16 v[4:7], v[116:119], v[192:195], v[4:7]
	v_mfma_f32_16x16x32_bf16 v[4:7], v[112:115], v[188:191], v[4:7]
	v_mfma_f32_16x16x32_bf16 v[0:3], v[138:141], v[188:191], v[0:3]
	v_mfma_f32_16x16x32_bf16 v[0:3], v[152:155], v[192:195], v[0:3]
	v_mfma_f32_16x16x32_bf16 v[16:19], v[152:155], v[184:187], v[16:19]
	v_mfma_f32_16x16x32_bf16 v[16:19], v[138:141], v[180:183], v[16:19]
	v_mfma_f32_16x16x32_bf16 v[32:35], v[138:141], v[172:175], v[32:35]
	v_mfma_f32_16x16x32_bf16 v[32:35], v[152:155], v[176:179], v[32:35]
	v_mfma_f32_16x16x32_bf16 v[48:51], v[152:155], v[168:171], v[48:51]
	v_mfma_f32_16x16x32_bf16 v[48:51], v[138:141], v[164:167], v[48:51]
	s_setprio 0
	s_barrier
	ds_read_b128 v[60:63], v136
	ds_read_b128 v[68:71], v136 offset:1024
	ds_read_b128 v[88:91], v136 offset:2048
	ds_read_b128 v[92:95], v136 offset:3072
	ds_read_b128 v[112:115], v137
	ds_read_b128 v[116:119], v137 offset:1024
	ds_read_b128 v[138:141], v137 offset:2048
	ds_read_b128 v[152:155], v137 offset:3072
	ds_read_b128 v[164:167], v214 offset:32768
	ds_read_b128 v[168:171], v214 offset:33792
	ds_read_b128 v[172:175], v214 offset:34816
	ds_read_b128 v[176:179], v214 offset:35840
	ds_read_b128 v[180:183], v214 offset:36864
	ds_read_b128 v[184:187], v214 offset:37888
	ds_read_b128 v[188:191], v214 offset:38912
	ds_read_b128 v[192:195], v214 offset:39936
	s_add_u32 s82, s2, 0x4000
	s_addc_u32 s83, s3, 0
	s_mov_b32 m0, s54
	s_nop 0
	global_load_lds_dwordx4 v210, s[82:83]
	s_add_u32 s82, s2, 0x6000
	s_addc_u32 s83, s3, 0
	s_mov_b32 m0, s55
	s_nop 0
	global_load_lds_dwordx4 v210, s[82:83]
	s_waitcnt vmcnt(8)
	s_waitcnt lgkmcnt(0)
	s_barrier
	s_setprio 1
	s_waitcnt lgkmcnt(7)
	s_waitcnt lgkmcnt(0)
	v_mfma_f32_16x16x32_bf16 v[160:163], v[60:63], v[164:167], v[160:163]
	v_mfma_f32_16x16x32_bf16 v[160:163], v[68:71], v[168:171], v[160:163]
	v_mfma_f32_16x16x32_bf16 v[132:135], v[68:71], v[176:179], v[132:135]
	v_mfma_f32_16x16x32_bf16 v[132:135], v[60:63], v[172:175], v[132:135]
	v_mfma_f32_16x16x32_bf16 v[108:111], v[60:63], v[180:183], v[108:111]
	v_mfma_f32_16x16x32_bf16 v[108:111], v[68:71], v[184:187], v[108:111]
	v_mfma_f32_16x16x32_bf16 v[84:87], v[68:71], v[192:195], v[84:87]
	v_mfma_f32_16x16x32_bf16 v[84:87], v[60:63], v[188:191], v[84:87]
	v_mfma_f32_16x16x32_bf16 v[80:83], v[88:91], v[188:191], v[80:83]
	v_mfma_f32_16x16x32_bf16 v[80:83], v[92:95], v[192:195], v[80:83]
	v_mfma_f32_16x16x32_bf16 v[104:107], v[92:95], v[184:187], v[104:107]
	v_mfma_f32_16x16x32_bf16 v[104:107], v[88:91], v[180:183], v[104:107]
	v_mfma_f32_16x16x32_bf16 v[128:131], v[88:91], v[172:175], v[128:131]
	v_mfma_f32_16x16x32_bf16 v[128:131], v[92:95], v[176:179], v[128:131]
	v_mfma_f32_16x16x32_bf16 v[156:159], v[92:95], v[168:171], v[156:159]
	v_mfma_f32_16x16x32_bf16 v[156:159], v[88:91], v[164:167], v[156:159]
	s_setprio 0
	s_setprio 1
	v_mfma_f32_16x16x32_bf16 v[146:149], v[112:115], v[164:167], v[148:151]
	v_mfma_f32_16x16x32_bf16 v[142:145], v[138:141], v[164:167], v[142:145]
	v_mfma_f32_16x16x32_bf16 v[124:127], v[112:115], v[172:175], v[124:127]
	v_mfma_f32_16x16x32_bf16 v[120:123], v[138:141], v[172:175], v[120:123]
	v_mfma_f32_16x16x32_bf16 v[100:103], v[112:115], v[180:183], v[100:103]
	v_mfma_f32_16x16x32_bf16 v[96:99], v[138:141], v[180:183], v[96:99]
	v_mfma_f32_16x16x32_bf16 v[76:79], v[112:115], v[188:191], v[76:79]
	v_mfma_f32_16x16x32_bf16 v[72:75], v[138:141], v[188:191], v[72:75]
	v_mfma_f32_16x16x32_bf16 v[148:151], v[116:119], v[168:171], v[146:149]
	v_mfma_f32_16x16x32_bf16 v[144:147], v[152:155], v[168:171], v[142:145]
	v_mfma_f32_16x16x32_bf16 v[124:127], v[116:119], v[176:179], v[124:127]
	v_mfma_f32_16x16x32_bf16 v[120:123], v[152:155], v[176:179], v[120:123]
	v_mfma_f32_16x16x32_bf16 v[100:103], v[116:119], v[184:187], v[100:103]
	v_mfma_f32_16x16x32_bf16 v[96:99], v[152:155], v[184:187], v[96:99]
	v_mfma_f32_16x16x32_bf16 v[76:79], v[116:119], v[192:195], v[76:79]
	v_mfma_f32_16x16x32_bf16 v[72:75], v[152:155], v[192:195], v[72:75]
	s_setprio 0
	s_barrier
	ds_read_b128 v[164:167], v214 offset:49152
	ds_read_b128 v[168:171], v214 offset:50176
	ds_read_b128 v[172:175], v214 offset:51200
	ds_read_b128 v[176:179], v214 offset:52224
	ds_read_b128 v[180:183], v214 offset:53248
	ds_read_b128 v[184:187], v214 offset:54272
	ds_read_b128 v[188:191], v214 offset:55296
	ds_read_b128 v[192:195], v214 offset:56320
	s_mov_b32 m0, s59
	s_nop 0
	global_load_lds_dwordx4 v210, s[44:45]
	s_add_u32 s44, s42, 0xa000
	s_addc_u32 s45, s43, 0
	s_mov_b32 m0, s60
	s_nop 0
	global_load_lds_dwordx4 v210, s[44:45]
	s_add_u32 s44, s42, 0xc000
	s_addc_u32 s45, s43, 0
	s_mov_b32 m0, s63
	s_nop 0
	global_load_lds_dwordx4 v210, s[44:45]
	s_add_u32 s42, s42, 0xe000
	s_addc_u32 s43, s43, 0
	s_mov_b32 m0, s64
	s_nop 0
	global_load_lds_dwordx4 v210, s[42:43]
	s_add_u32 s2, s2, 0xa000
	s_mov_b32 m0, s61
	s_nop 0
	global_load_lds_dwordx4 v210, s[40:41]
	s_addc_u32 s3, s3, 0
	s_mov_b32 m0, s62
	s_nop 0
	global_load_lds_dwordx4 v210, s[2:3]
	s_waitcnt vmcnt(8)
	s_waitcnt lgkmcnt(0)
	s_barrier
	s_setprio 1
	s_waitcnt lgkmcnt(7)
	s_waitcnt lgkmcnt(0)
	v_mfma_f32_16x16x32_bf16 v[64:67], v[60:63], v[164:167], v[64:67]
	v_mfma_f32_16x16x32_bf16 v[64:67], v[68:71], v[168:171], v[64:67]
	v_mfma_f32_16x16x32_bf16 v[44:47], v[68:71], v[176:179], v[44:47]
	v_mfma_f32_16x16x32_bf16 v[44:47], v[60:63], v[172:175], v[44:47]
	v_mfma_f32_16x16x32_bf16 v[28:31], v[60:63], v[180:183], v[28:31]
	v_mfma_f32_16x16x32_bf16 v[28:31], v[68:71], v[184:187], v[28:31]
	v_mfma_f32_16x16x32_bf16 v[12:15], v[68:71], v[192:195], v[12:15]
	v_mfma_f32_16x16x32_bf16 v[12:15], v[60:63], v[188:191], v[12:15]
	v_mfma_f32_16x16x32_bf16 v[8:11], v[88:91], v[188:191], v[8:11]
	v_mfma_f32_16x16x32_bf16 v[8:11], v[92:95], v[192:195], v[8:11]
	v_mfma_f32_16x16x32_bf16 v[24:27], v[92:95], v[184:187], v[24:27]
	v_mfma_f32_16x16x32_bf16 v[24:27], v[88:91], v[180:183], v[24:27]
	v_mfma_f32_16x16x32_bf16 v[40:43], v[88:91], v[172:175], v[40:43]
	v_mfma_f32_16x16x32_bf16 v[40:43], v[92:95], v[176:179], v[40:43]
	v_mfma_f32_16x16x32_bf16 v[56:59], v[92:95], v[168:171], v[56:59]
	v_mfma_f32_16x16x32_bf16 v[56:59], v[88:91], v[164:167], v[56:59]
	s_setprio 0
	s_setprio 1
	s_waitcnt lgkmcnt(0)
	v_mfma_f32_16x16x32_bf16 v[52:55], v[112:115], v[164:167], v[52:55]
	v_mfma_f32_16x16x32_bf16 v[52:55], v[116:119], v[168:171], v[52:55]
	v_mfma_f32_16x16x32_bf16 v[36:39], v[116:119], v[176:179], v[36:39]
	v_mfma_f32_16x16x32_bf16 v[36:39], v[112:115], v[172:175], v[36:39]
	v_mfma_f32_16x16x32_bf16 v[20:23], v[112:115], v[180:183], v[20:23]
	v_mfma_f32_16x16x32_bf16 v[20:23], v[116:119], v[184:187], v[20:23]
	v_mfma_f32_16x16x32_bf16 v[4:7], v[116:119], v[192:195], v[4:7]
	v_mfma_f32_16x16x32_bf16 v[4:7], v[112:115], v[188:191], v[4:7]
	v_mfma_f32_16x16x32_bf16 v[0:3], v[138:141], v[188:191], v[0:3]
	v_mfma_f32_16x16x32_bf16 v[0:3], v[152:155], v[192:195], v[0:3]
	v_mfma_f32_16x16x32_bf16 v[16:19], v[152:155], v[184:187], v[16:19]
	v_mfma_f32_16x16x32_bf16 v[16:19], v[138:141], v[180:183], v[16:19]
	v_mfma_f32_16x16x32_bf16 v[32:35], v[138:141], v[172:175], v[32:35]
	v_mfma_f32_16x16x32_bf16 v[32:35], v[152:155], v[176:179], v[32:35]
	v_mfma_f32_16x16x32_bf16 v[48:51], v[152:155], v[168:171], v[48:51]
	v_mfma_f32_16x16x32_bf16 v[48:51], v[138:141], v[164:167], v[48:51]
	s_setprio 0
	s_barrier
	s_add_i32 s80, s80, 2
	s_add_u32 s76, s76, 0x10000
	s_addc_u32 s77, s77, 0
	s_add_u32 s78, s78, 0x10000
	s_addc_u32 s79, s79, 0
	s_cmpk_gt_u32 s80, 0xa9
	s_cbranch_scc0 .LBB0_326
	s_and_b64 vcc, exec, s[12:13]
	s_cbranch_vccz .LBB0_329
	s_barrier

.LBB0_425:
	ds_read_b128 v[128:131], v162
	ds_read_b128 v[132:135], v162 offset:1024
	ds_read_b128 v[136:139], v162 offset:2048
	ds_read_b128 v[140:143], v162 offset:3072
	ds_read_b128 v[152:155], v163
	ds_read_b128 v[156:159], v163 offset:1024
	ds_read_b128 v[168:171], v163 offset:2048
	ds_read_b128 v[172:175], v163 offset:3072
	s_add_u32 s48, s52, 0x10000
	s_addc_u32 s49, s53, 0
	s_cmp_eq_u32 s79, 60
	s_cselect_b32 s80, s10, s48
	s_cselect_b32 s81, s5, s49
	s_cselect_b32 s96, s47, s77
	s_cselect_b32 s97, s45, s78
	s_add_u32 s2, s80, 0x8000
	s_addc_u32 s3, s81, 0
	ds_read_b128 v[176:179], v164
	ds_read_b128 v[180:183], v164 offset:1024
	ds_read_b128 v[184:187], v164 offset:2048
	ds_read_b128 v[188:191], v164 offset:3072
	ds_read_b128 v[192:195], v164 offset:4096
	ds_read_b128 v[196:199], v164 offset:5120
	ds_read_b128 v[200:203], v164 offset:6144
	ds_read_b128 v[204:207], v164 offset:7168
	s_add_u32 s82, s52, 0xc000
	s_addc_u32 s83, s53, 0
	s_mov_b32 m0, s70
	s_nop 0
	global_load_lds_dwordx4 v160, s[82:83]
	s_add_u32 s52, s52, 0xe000
	s_addc_u32 s53, s53, 0
	s_mov_b32 m0, s71
	s_nop 0
	global_load_lds_dwordx4 v160, s[52:53]
	s_waitcnt vmcnt(8)
	s_waitcnt lgkmcnt(0)
	s_add_u32 s52, s96, 0x8000
	s_addc_u32 s53, s97, 0
	s_barrier
	s_setprio 1
	s_waitcnt lgkmcnt(7)
	s_waitcnt lgkmcnt(0)
	v_mfma_f32_16x16x32_bf16 v[124:127], v[128:131], v[176:179], v[124:127]
	v_mfma_f32_16x16x32_bf16 v[124:127], v[132:135], v[180:183], v[124:127]
	v_mfma_f32_16x16x32_bf16 v[108:111], v[132:135], v[188:191], v[108:111]
	v_mfma_f32_16x16x32_bf16 v[108:111], v[128:131], v[184:187], v[108:111]
	v_mfma_f32_16x16x32_bf16 v[92:95], v[128:131], v[192:195], v[92:95]
	v_mfma_f32_16x16x32_bf16 v[92:95], v[132:135], v[196:199], v[92:95]
	v_mfma_f32_16x16x32_bf16 v[76:79], v[132:135], v[204:207], v[76:79]
	v_mfma_f32_16x16x32_bf16 v[76:79], v[128:131], v[200:203], v[76:79]
	v_mfma_f32_16x16x32_bf16 v[72:75], v[136:139], v[200:203], v[72:75]
	v_mfma_f32_16x16x32_bf16 v[72:75], v[140:143], v[204:207], v[72:75]
	v_mfma_f32_16x16x32_bf16 v[88:91], v[140:143], v[196:199], v[88:91]
	v_mfma_f32_16x16x32_bf16 v[88:91], v[136:139], v[192:195], v[88:91]
	v_mfma_f32_16x16x32_bf16 v[104:107], v[136:139], v[184:187], v[104:107]
	v_mfma_f32_16x16x32_bf16 v[104:107], v[140:143], v[188:191], v[104:107]
	v_mfma_f32_16x16x32_bf16 v[120:123], v[140:143], v[180:183], v[120:123]
	v_mfma_f32_16x16x32_bf16 v[120:123], v[136:139], v[176:179], v[120:123]
	s_setprio 0
	s_setprio 1
	s_waitcnt lgkmcnt(0)
	v_mfma_f32_16x16x32_bf16 v[116:119], v[152:155], v[176:179], v[116:119]
	v_mfma_f32_16x16x32_bf16 v[116:119], v[156:159], v[180:183], v[116:119]
	v_mfma_f32_16x16x32_bf16 v[100:103], v[156:159], v[188:191], v[100:103]
	v_mfma_f32_16x16x32_bf16 v[100:103], v[152:155], v[184:187], v[100:103]
	v_mfma_f32_16x16x32_bf16 v[84:87], v[152:155], v[192:195], v[84:87]
	v_mfma_f32_16x16x32_bf16 v[84:87], v[156:159], v[196:199], v[84:87]
	v_mfma_f32_16x16x32_bf16 v[68:71], v[156:159], v[204:207], v[68:71]
	v_mfma_f32_16x16x32_bf16 v[68:71], v[152:155], v[200:203], v[68:71]
	v_mfma_f32_16x16x32_bf16 v[64:67], v[168:171], v[200:203], v[64:67]
	v_mfma_f32_16x16x32_bf16 v[64:67], v[172:175], v[204:207], v[64:67]
	v_mfma_f32_16x16x32_bf16 v[80:83], v[172:175], v[196:199], v[80:83]
	v_mfma_f32_16x16x32_bf16 v[80:83], v[168:171], v[192:195], v[80:83]
	v_mfma_f32_16x16x32_bf16 v[96:99], v[168:171], v[184:187], v[96:99]
	v_mfma_f32_16x16x32_bf16 v[96:99], v[172:175], v[188:191], v[96:99]
	v_mfma_f32_16x16x32_bf16 v[112:115], v[172:175], v[180:183], v[112:115]
	v_mfma_f32_16x16x32_bf16 v[112:115], v[168:171], v[176:179], v[112:115]
	s_setprio 0
	s_barrier
	s_add_u32 s82, s96, 0x2000
	ds_read_b128 v[176:179], v164 offset:16384
	ds_read_b128 v[180:183], v164 offset:17408
	ds_read_b128 v[184:187], v164 offset:18432
	ds_read_b128 v[188:191], v164 offset:19456
	ds_read_b128 v[192:195], v164 offset:20480
	ds_read_b128 v[196:199], v164 offset:21504
	ds_read_b128 v[200:203], v164 offset:22528
	ds_read_b128 v[204:207], v164 offset:23552
	s_mov_b32 m0, s55
	s_nop 0
	global_load_lds_dwordx4 v160, s[96:97]
	s_addc_u32 s83, s97, 0
	s_mov_b32 m0, s56
	s_nop 0
	global_load_lds_dwordx4 v160, s[82:83]
	s_add_u32 s82, s96, 0x4000
	s_addc_u32 s83, s97, 0
	s_mov_b32 m0, s57
	s_nop 0
	global_load_lds_dwordx4 v160, s[82:83]
	s_add_u32 s82, s96, 0x6000
	s_addc_u32 s83, s97, 0
	s_mov_b32 m0, s58
	s_nop 0
	global_load_lds_dwordx4 v160, s[82:83]
	s_add_u32 s82, s80, 0x2000
	s_mov_b32 m0, s54
	s_nop 0
	global_load_lds_dwordx4 v160, s[80:81]
	s_addc_u32 s83, s81, 0
	s_mov_b32 m0, s59
	s_nop 0
	global_load_lds_dwordx4 v160, s[82:83]
	s_waitcnt vmcnt(8)
	s_waitcnt lgkmcnt(0)
	s_barrier
	s_setprio 1
	s_waitcnt lgkmcnt(7)
	s_waitcnt lgkmcnt(0)
	v_mfma_f32_16x16x32_bf16 v[60:63], v[128:131], v[176:179], v[60:63]
	v_mfma_f32_16x16x32_bf16 v[60:63], v[132:135], v[180:183], v[60:63]
	v_mfma_f32_16x16x32_bf16 v[44:47], v[132:135], v[188:191], v[44:47]
	v_mfma_f32_16x16x32_bf16 v[44:47], v[128:131], v[184:187], v[44:47]
	v_mfma_f32_16x16x32_bf16 v[28:31], v[128:131], v[192:195], v[28:31]
	v_mfma_f32_16x16x32_bf16 v[28:31], v[132:135], v[196:199], v[28:31]
	v_mfma_f32_16x16x32_bf16 v[12:15], v[132:135], v[204:207], v[12:15]
	v_mfma_f32_16x16x32_bf16 v[12:15], v[128:131], v[200:203], v[12:15]
	v_mfma_f32_16x16x32_bf16 v[8:11], v[136:139], v[200:203], v[8:11]
	v_mfma_f32_16x16x32_bf16 v[8:11], v[140:143], v[204:207], v[8:11]
	v_mfma_f32_16x16x32_bf16 v[24:27], v[140:143], v[196:199], v[24:27]
	v_mfma_f32_16x16x32_bf16 v[24:27], v[136:139], v[192:195], v[24:27]
	v_mfma_f32_16x16x32_bf16 v[40:43], v[136:139], v[184:187], v[40:43]
	v_mfma_f32_16x16x32_bf16 v[40:43], v[140:143], v[188:191], v[40:43]
	v_mfma_f32_16x16x32_bf16 v[56:59], v[140:143], v[180:183], v[56:59]
	v_mfma_f32_16x16x32_bf16 v[56:59], v[136:139], v[176:179], v[56:59]
	s_setprio 0
	s_setprio 1
	s_waitcnt lgkmcnt(0)
	v_mfma_f32_16x16x32_bf16 v[52:55], v[152:155], v[176:179], v[52:55]
	v_mfma_f32_16x16x32_bf16 v[52:55], v[156:159], v[180:183], v[52:55]
	v_mfma_f32_16x16x32_bf16 v[36:39], v[156:159], v[188:191], v[36:39]
	v_mfma_f32_16x16x32_bf16 v[36:39], v[152:155], v[184:187], v[36:39]
	v_mfma_f32_16x16x32_bf16 v[20:23], v[152:155], v[192:195], v[20:23]
	v_mfma_f32_16x16x32_bf16 v[20:23], v[156:159], v[196:199], v[20:23]
	v_mfma_f32_16x16x32_bf16 v[4:7], v[156:159], v[204:207], v[4:7]
	v_mfma_f32_16x16x32_bf16 v[4:7], v[152:155], v[200:203], v[4:7]
	v_mfma_f32_16x16x32_bf16 v[0:3], v[168:171], v[200:203], v[0:3]
	v_mfma_f32_16x16x32_bf16 v[0:3], v[172:175], v[204:207], v[0:3]
	v_mfma_f32_16x16x32_bf16 v[16:19], v[172:175], v[196:199], v[16:19]
	v_mfma_f32_16x16x32_bf16 v[16:19], v[168:171], v[192:195], v[16:19]
	v_mfma_f32_16x16x32_bf16 v[32:35], v[168:171], v[184:187], v[32:35]
	v_mfma_f32_16x16x32_bf16 v[32:35], v[172:175], v[188:191], v[32:35]
	v_mfma_f32_16x16x32_bf16 v[48:51], v[172:175], v[180:183], v[48:51]
	v_mfma_f32_16x16x32_bf16 v[48:51], v[168:171], v[176:179], v[48:51]
	s_setprio 0
	s_barrier
	ds_read_b128 v[128:131], v148
	ds_read_b128 v[132:135], v148 offset:1024
	ds_read_b128 v[136:139], v148 offset:2048
	ds_read_b128 v[140:143], v148 offset:3072
	ds_read_b128 v[152:155], v150
	ds_read_b128 v[156:159], v150 offset:1024
	ds_read_b128 v[168:171], v150 offset:2048
	ds_read_b128 v[172:175], v150 offset:3072
	ds_read_b128 v[176:179], v164 offset:32768
	ds_read_b128 v[180:183], v164 offset:33792
	ds_read_b128 v[184:187], v164 offset:34816
	ds_read_b128 v[188:191], v164 offset:35840
	ds_read_b128 v[192:195], v164 offset:36864
	ds_read_b128 v[196:199], v164 offset:37888
	ds_read_b128 v[200:203], v164 offset:38912
	ds_read_b128 v[204:207], v164 offset:39936
	s_add_u32 s82, s80, 0x4000
	s_addc_u32 s83, s81, 0
	s_mov_b32 m0, s60
	s_nop 0
	global_load_lds_dwordx4 v160, s[82:83]
	s_add_u32 s82, s80, 0x6000
	s_addc_u32 s83, s81, 0
	s_mov_b32 m0, s61
	s_nop 0
	global_load_lds_dwordx4 v160, s[82:83]
	s_waitcnt vmcnt(8)
	s_waitcnt lgkmcnt(0)
	s_barrier
	s_setprio 1
	s_waitcnt lgkmcnt(7)
	s_waitcnt lgkmcnt(0)
	v_mfma_f32_16x16x32_bf16 v[124:127], v[128:131], v[176:179], v[124:127]
	v_mfma_f32_16x16x32_bf16 v[124:127], v[132:135], v[180:183], v[124:127]
	v_mfma_f32_16x16x32_bf16 v[108:111], v[132:135], v[188:191], v[108:111]
	v_mfma_f32_16x16x32_bf16 v[108:111], v[128:131], v[184:187], v[108:111]
	v_mfma_f32_16x16x32_bf16 v[92:95], v[128:131], v[192:195], v[92:95]
	v_mfma_f32_16x16x32_bf16 v[92:95], v[132:135], v[196:199], v[92:95]
	v_mfma_f32_16x16x32_bf16 v[76:79], v[132:135], v[204:207], v[76:79]
	v_mfma_f32_16x16x32_bf16 v[76:79], v[128:131], v[200:203], v[76:79]
	v_mfma_f32_16x16x32_bf16 v[72:75], v[136:139], v[200:203], v[72:75]
	v_mfma_f32_16x16x32_bf16 v[72:75], v[140:143], v[204:207], v[72:75]
	v_mfma_f32_16x16x32_bf16 v[88:91], v[140:143], v[196:199], v[88:91]
	v_mfma_f32_16x16x32_bf16 v[88:91], v[136:139], v[192:195], v[88:91]
	v_mfma_f32_16x16x32_bf16 v[104:107], v[136:139], v[184:187], v[104:107]
	v_mfma_f32_16x16x32_bf16 v[104:107], v[140:143], v[188:191], v[104:107]
	v_mfma_f32_16x16x32_bf16 v[120:123], v[140:143], v[180:183], v[120:123]
	v_mfma_f32_16x16x32_bf16 v[120:123], v[136:139], v[176:179], v[120:123]
	s_setprio 0
	s_setprio 1
	s_waitcnt lgkmcnt(0)
	v_mfma_f32_16x16x32_bf16 v[116:119], v[152:155], v[176:179], v[116:119]
	v_mfma_f32_16x16x32_bf16 v[116:119], v[156:159], v[180:183], v[116:119]
	v_mfma_f32_16x16x32_bf16 v[100:103], v[156:159], v[188:191], v[100:103]
	v_mfma_f32_16x16x32_bf16 v[100:103], v[152:155], v[184:187], v[100:103]
	v_mfma_f32_16x16x32_bf16 v[84:87], v[152:155], v[192:195], v[84:87]
	v_mfma_f32_16x16x32_bf16 v[84:87], v[156:159], v[196:199], v[84:87]
	v_mfma_f32_16x16x32_bf16 v[68:71], v[156:159], v[204:207], v[68:71]
	v_mfma_f32_16x16x32_bf16 v[68:71], v[152:155], v[200:203], v[68:71]
	v_mfma_f32_16x16x32_bf16 v[64:67], v[168:171], v[200:203], v[64:67]
	v_mfma_f32_16x16x32_bf16 v[64:67], v[172:175], v[204:207], v[64:67]
	v_mfma_f32_16x16x32_bf16 v[80:83], v[172:175], v[196:199], v[80:83]
	v_mfma_f32_16x16x32_bf16 v[80:83], v[168:171], v[192:195], v[80:83]
	v_mfma_f32_16x16x32_bf16 v[96:99], v[168:171], v[184:187], v[96:99]
	v_mfma_f32_16x16x32_bf16 v[96:99], v[172:175], v[188:191], v[96:99]
	v_mfma_f32_16x16x32_bf16 v[112:115], v[172:175], v[180:183], v[112:115]
	v_mfma_f32_16x16x32_bf16 v[112:115], v[168:171], v[176:179], v[112:115]
	s_setprio 0
	s_barrier
	ds_read_b128 v[176:179], v164 offset:49152
	ds_read_b128 v[180:183], v164 offset:50176
	ds_read_b128 v[184:187], v164 offset:51200
	ds_read_b128 v[188:191], v164 offset:52224
	ds_read_b128 v[192:195], v164 offset:53248
	ds_read_b128 v[196:199], v164 offset:54272
	ds_read_b128 v[200:203], v164 offset:55296
	ds_read_b128 v[204:207], v164 offset:56320
	s_mov_b32 m0, s64
	s_nop 0
	global_load_lds_dwordx4 v160, s[52:53]
	s_add_u32 s52, s96, 0xa000
	s_addc_u32 s53, s97, 0
	s_mov_b32 m0, s65
	s_nop 0
	global_load_lds_dwordx4 v160, s[52:53]
	s_add_u32 s52, s96, 0xc000
	s_addc_u32 s53, s97, 0
	s_mov_b32 m0, s68
	s_nop 0
	global_load_lds_dwordx4 v160, s[52:53]
	s_add_u32 s52, s96, 0xe000
	s_addc_u32 s53, s97, 0
	s_mov_b32 m0, s69
	s_nop 0
	global_load_lds_dwordx4 v160, s[52:53]
	s_nop 0
	s_mov_b32 m0, s66
	s_nop 0
	global_load_lds_dwordx4 v160, s[2:3]
	s_add_u32 s2, s80, 0xa000
	s_addc_u32 s3, s81, 0
	s_mov_b32 m0, s67
	s_nop 0
	global_load_lds_dwordx4 v160, s[2:3]
	s_waitcnt vmcnt(8)
	s_waitcnt lgkmcnt(0)
	s_barrier
	s_setprio 1
	s_waitcnt lgkmcnt(7)
	s_waitcnt lgkmcnt(0)
	v_mfma_f32_16x16x32_bf16 v[60:63], v[128:131], v[176:179], v[60:63]
	v_mfma_f32_16x16x32_bf16 v[60:63], v[132:135], v[180:183], v[60:63]
	v_mfma_f32_16x16x32_bf16 v[44:47], v[132:135], v[188:191], v[44:47]
	v_mfma_f32_16x16x32_bf16 v[44:47], v[128:131], v[184:187], v[44:47]
	v_mfma_f32_16x16x32_bf16 v[28:31], v[128:131], v[192:195], v[28:31]
	v_mfma_f32_16x16x32_bf16 v[28:31], v[132:135], v[196:199], v[28:31]
	v_mfma_f32_16x16x32_bf16 v[12:15], v[132:135], v[204:207], v[12:15]
	v_mfma_f32_16x16x32_bf16 v[12:15], v[128:131], v[200:203], v[12:15]
	v_mfma_f32_16x16x32_bf16 v[8:11], v[136:139], v[200:203], v[8:11]
	v_mfma_f32_16x16x32_bf16 v[8:11], v[140:143], v[204:207], v[8:11]
	v_mfma_f32_16x16x32_bf16 v[24:27], v[140:143], v[196:199], v[24:27]
	v_mfma_f32_16x16x32_bf16 v[24:27], v[136:139], v[192:195], v[24:27]
	v_mfma_f32_16x16x32_bf16 v[40:43], v[136:139], v[184:187], v[40:43]
	v_mfma_f32_16x16x32_bf16 v[40:43], v[140:143], v[188:191], v[40:43]
	v_mfma_f32_16x16x32_bf16 v[56:59], v[140:143], v[180:183], v[56:59]
	v_mfma_f32_16x16x32_bf16 v[56:59], v[136:139], v[176:179], v[56:59]
	s_setprio 0
	s_setprio 1
	s_waitcnt lgkmcnt(0)
	v_mfma_f32_16x16x32_bf16 v[52:55], v[152:155], v[176:179], v[52:55]
	v_mfma_f32_16x16x32_bf16 v[52:55], v[156:159], v[180:183], v[52:55]
	v_mfma_f32_16x16x32_bf16 v[36:39], v[156:159], v[188:191], v[36:39]
	v_mfma_f32_16x16x32_bf16 v[36:39], v[152:155], v[184:187], v[36:39]
	v_mfma_f32_16x16x32_bf16 v[20:23], v[152:155], v[192:195], v[20:23]
	v_mfma_f32_16x16x32_bf16 v[20:23], v[156:159], v[196:199], v[20:23]
	v_mfma_f32_16x16x32_bf16 v[4:7], v[156:159], v[204:207], v[4:7]
	v_mfma_f32_16x16x32_bf16 v[4:7], v[152:155], v[200:203], v[4:7]
	v_mfma_f32_16x16x32_bf16 v[0:3], v[168:171], v[200:203], v[0:3]
	v_mfma_f32_16x16x32_bf16 v[0:3], v[172:175], v[204:207], v[0:3]
	v_mfma_f32_16x16x32_bf16 v[16:19], v[172:175], v[196:199], v[16:19]
	v_mfma_f32_16x16x32_bf16 v[16:19], v[168:171], v[192:195], v[16:19]
	v_mfma_f32_16x16x32_bf16 v[32:35], v[168:171], v[184:187], v[32:35]
	v_mfma_f32_16x16x32_bf16 v[32:35], v[172:175], v[188:191], v[32:35]
	v_mfma_f32_16x16x32_bf16 v[48:51], v[172:175], v[180:183], v[48:51]
	v_mfma_f32_16x16x32_bf16 v[48:51], v[168:171], v[176:179], v[48:51]
	s_setprio 0
	s_barrier
	s_add_i32 s79, s79, 2
	s_add_u32 s77, s77, 0x10000
	s_addc_u32 s78, s78, 0
	s_cmp_gt_u32 s79, 61
	s_mov_b64 s[52:53], s[48:49]
	s_cbranch_scc0 .LBB0_425
	s_and_b64 vcc, exec, s[14:15]
	s_cbranch_vccz .LBB0_428
	s_barrier

.LBB0_1406:
	ds_read_b128 v[72:75], v212
	ds_read_b128 v[84:87], v212 offset:1024
	ds_read_b128 v[96:99], v212 offset:2048
	ds_read_b128 v[108:111], v212 offset:3072
	ds_read_b128 v[112:115], v213
	ds_read_b128 v[136:139], v213 offset:1024
	ds_read_b128 v[148:151], v213 offset:2048
	ds_read_b128 v[160:163], v213 offset:3072
	s_cmp_eq_u32 s90, 60
	s_cselect_b32 s2, s82, s54
	s_cselect_b32 s3, s41, s55
	s_cselect_b32 s58, s83, s88
	s_cselect_b32 s59, s39, s89
	s_add_u32 s56, s2, 0x8000
	s_addc_u32 s57, s3, 0
	ds_read_b128 v[164:167], v214
	ds_read_b128 v[168:171], v214 offset:1024
	ds_read_b128 v[172:175], v214 offset:2048
	ds_read_b128 v[176:179], v214 offset:3072
	ds_read_b128 v[180:183], v214 offset:4096
	ds_read_b128 v[184:187], v214 offset:5120
	ds_read_b128 v[188:191], v214 offset:6144
	ds_read_b128 v[192:195], v214 offset:7168
	s_add_u32 s52, s54, 0xffffc000
	s_addc_u32 s53, s55, -1
	s_mov_b32 m0, s75
	s_nop 0
	global_load_lds_dwordx4 v210, s[52:53]
	s_add_u32 s52, s54, 0xffffe000
	s_addc_u32 s53, s55, -1
	s_mov_b32 m0, s78
	s_nop 0
	global_load_lds_dwordx4 v210, s[52:53]
	s_waitcnt vmcnt(8)
	s_waitcnt lgkmcnt(0)
	s_add_u32 s52, s58, 0x8000
	s_addc_u32 s53, s59, 0
	s_barrier
	s_setprio 1
	s_waitcnt lgkmcnt(7)
	v_mfma_f32_16x16x32_bf16 v[156:159], v[72:75], v[164:167], v[156:159]
	v_mfma_f32_16x16x32_bf16 v[152:155], v[96:99], v[164:167], v[152:155]
	s_waitcnt lgkmcnt(5)
	v_mfma_f32_16x16x32_bf16 v[132:135], v[72:75], v[172:175], v[132:135]
	v_mfma_f32_16x16x32_bf16 v[126:129], v[96:99], v[172:175], v[128:131]
	s_waitcnt lgkmcnt(3)
	v_mfma_f32_16x16x32_bf16 v[104:107], v[72:75], v[180:183], v[104:107]
	v_mfma_f32_16x16x32_bf16 v[100:103], v[96:99], v[180:183], v[100:103]
	s_waitcnt lgkmcnt(1)
	v_mfma_f32_16x16x32_bf16 v[80:83], v[72:75], v[188:191], v[80:83]
	v_mfma_f32_16x16x32_bf16 v[76:79], v[96:99], v[188:191], v[76:79]
	v_mfma_f32_16x16x32_bf16 v[156:159], v[84:87], v[168:171], v[156:159]
	v_mfma_f32_16x16x32_bf16 v[152:155], v[108:111], v[168:171], v[152:155]
	v_mfma_f32_16x16x32_bf16 v[132:135], v[84:87], v[176:179], v[132:135]
	v_mfma_f32_16x16x32_bf16 v[126:129], v[108:111], v[176:179], v[126:129]
	v_mfma_f32_16x16x32_bf16 v[104:107], v[84:87], v[184:187], v[104:107]
	v_mfma_f32_16x16x32_bf16 v[100:103], v[108:111], v[184:187], v[100:103]
	s_waitcnt lgkmcnt(0)
	v_mfma_f32_16x16x32_bf16 v[80:83], v[84:87], v[192:195], v[80:83]
	v_mfma_f32_16x16x32_bf16 v[76:79], v[108:111], v[192:195], v[76:79]
	s_setprio 0
	s_setprio 1
	s_waitcnt lgkmcnt(0)
	v_mfma_f32_16x16x32_bf16 v[144:147], v[112:115], v[164:167], v[144:147]
	v_mfma_f32_16x16x32_bf16 v[144:147], v[136:139], v[168:171], v[144:147]
	v_mfma_f32_16x16x32_bf16 v[120:123], v[136:139], v[176:179], v[120:123]
	v_mfma_f32_16x16x32_bf16 v[120:123], v[112:115], v[172:175], v[120:123]
	v_mfma_f32_16x16x32_bf16 v[92:95], v[112:115], v[180:183], v[92:95]
	v_mfma_f32_16x16x32_bf16 v[92:95], v[136:139], v[184:187], v[92:95]
	v_mfma_f32_16x16x32_bf16 v[68:71], v[136:139], v[192:195], v[68:71]
	v_mfma_f32_16x16x32_bf16 v[68:71], v[112:115], v[188:191], v[68:71]
	v_mfma_f32_16x16x32_bf16 v[64:67], v[148:151], v[188:191], v[64:67]
	v_mfma_f32_16x16x32_bf16 v[64:67], v[160:163], v[192:195], v[64:67]
	v_mfma_f32_16x16x32_bf16 v[88:91], v[160:163], v[184:187], v[88:91]
	v_mfma_f32_16x16x32_bf16 v[88:91], v[148:151], v[180:183], v[88:91]
	v_mfma_f32_16x16x32_bf16 v[116:119], v[148:151], v[172:175], v[116:119]
	v_mfma_f32_16x16x32_bf16 v[116:119], v[160:163], v[176:179], v[116:119]
	v_mfma_f32_16x16x32_bf16 v[140:143], v[160:163], v[168:171], v[140:143]
	v_mfma_f32_16x16x32_bf16 v[140:143], v[148:151], v[164:167], v[140:143]
	s_setprio 0
	s_barrier
	s_add_u32 s92, s58, 0x2000
	ds_read_b128 v[164:167], v214 offset:16384
	ds_read_b128 v[168:171], v214 offset:17408
	ds_read_b128 v[172:175], v214 offset:18432
	ds_read_b128 v[176:179], v214 offset:19456
	ds_read_b128 v[180:183], v214 offset:20480
	ds_read_b128 v[184:187], v214 offset:21504
	ds_read_b128 v[188:191], v214 offset:22528
	ds_read_b128 v[192:195], v214 offset:23552
	s_mov_b32 m0, s47
	s_nop 0
	global_load_lds_dwordx4 v210, s[58:59]
	s_addc_u32 s93, s59, 0
	s_mov_b32 m0, s49
	s_nop 0
	global_load_lds_dwordx4 v210, s[92:93]
	s_add_u32 s92, s58, 0x4000
	s_addc_u32 s93, s59, 0
	s_mov_b32 m0, s61
	s_nop 0
	global_load_lds_dwordx4 v210, s[92:93]
	s_add_u32 s92, s58, 0x6000
	s_addc_u32 s93, s59, 0
	s_mov_b32 m0, s62
	s_nop 0
	global_load_lds_dwordx4 v210, s[92:93]
	s_add_u32 s92, s2, 0x2000
	s_mov_b32 m0, s60
	s_nop 0
	global_load_lds_dwordx4 v210, s[2:3]
	s_addc_u32 s93, s3, 0
	s_mov_b32 m0, s63
	s_nop 0
	global_load_lds_dwordx4 v210, s[92:93]
	s_waitcnt vmcnt(8)
	s_waitcnt lgkmcnt(0)
	s_barrier
	s_setprio 1
	s_waitcnt lgkmcnt(7)
	s_waitcnt lgkmcnt(0)
	v_mfma_f32_16x16x32_bf16 v[60:63], v[72:75], v[164:167], v[60:63]
	v_mfma_f32_16x16x32_bf16 v[60:63], v[84:87], v[168:171], v[60:63]
	v_mfma_f32_16x16x32_bf16 v[44:47], v[84:87], v[176:179], v[44:47]
	v_mfma_f32_16x16x32_bf16 v[44:47], v[72:75], v[172:175], v[44:47]
	v_mfma_f32_16x16x32_bf16 v[28:31], v[72:75], v[180:183], v[28:31]
	v_mfma_f32_16x16x32_bf16 v[28:31], v[84:87], v[184:187], v[28:31]
	v_mfma_f32_16x16x32_bf16 v[12:15], v[84:87], v[192:195], v[12:15]
	v_mfma_f32_16x16x32_bf16 v[12:15], v[72:75], v[188:191], v[12:15]
	v_mfma_f32_16x16x32_bf16 v[8:11], v[96:99], v[188:191], v[8:11]
	v_mfma_f32_16x16x32_bf16 v[8:11], v[108:111], v[192:195], v[8:11]
	v_mfma_f32_16x16x32_bf16 v[24:27], v[108:111], v[184:187], v[24:27]
	v_mfma_f32_16x16x32_bf16 v[24:27], v[96:99], v[180:183], v[24:27]
	v_mfma_f32_16x16x32_bf16 v[40:43], v[96:99], v[172:175], v[40:43]
	v_mfma_f32_16x16x32_bf16 v[40:43], v[108:111], v[176:179], v[40:43]
	v_mfma_f32_16x16x32_bf16 v[56:59], v[108:111], v[168:171], v[56:59]
	v_mfma_f32_16x16x32_bf16 v[56:59], v[96:99], v[164:167], v[56:59]
	s_setprio 0
	s_setprio 1
	s_waitcnt lgkmcnt(0)
	v_mfma_f32_16x16x32_bf16 v[52:55], v[112:115], v[164:167], v[52:55]
	v_mfma_f32_16x16x32_bf16 v[52:55], v[136:139], v[168:171], v[52:55]
	v_mfma_f32_16x16x32_bf16 v[36:39], v[136:139], v[176:179], v[36:39]
	v_mfma_f32_16x16x32_bf16 v[36:39], v[112:115], v[172:175], v[36:39]
	v_mfma_f32_16x16x32_bf16 v[20:23], v[112:115], v[180:183], v[20:23]
	v_mfma_f32_16x16x32_bf16 v[20:23], v[136:139], v[184:187], v[20:23]
	v_mfma_f32_16x16x32_bf16 v[4:7], v[136:139], v[192:195], v[4:7]
	v_mfma_f32_16x16x32_bf16 v[4:7], v[112:115], v[188:191], v[4:7]
	v_mfma_f32_16x16x32_bf16 v[0:3], v[148:151], v[188:191], v[0:3]
	v_mfma_f32_16x16x32_bf16 v[0:3], v[160:163], v[192:195], v[0:3]
	v_mfma_f32_16x16x32_bf16 v[16:19], v[160:163], v[184:187], v[16:19]
	v_mfma_f32_16x16x32_bf16 v[16:19], v[148:151], v[180:183], v[16:19]
	v_mfma_f32_16x16x32_bf16 v[32:35], v[148:151], v[172:175], v[32:35]
	v_mfma_f32_16x16x32_bf16 v[32:35], v[160:163], v[176:179], v[32:35]
	v_mfma_f32_16x16x32_bf16 v[48:51], v[160:163], v[168:171], v[48:51]
	v_mfma_f32_16x16x32_bf16 v[48:51], v[148:151], v[164:167], v[48:51]
	s_setprio 0
	s_barrier
	ds_read_b128 v[72:75], v124
	ds_read_b128 v[84:87], v124 offset:1024
	ds_read_b128 v[96:99], v124 offset:2048
	ds_read_b128 v[108:111], v124 offset:3072
	ds_read_b128 v[112:115], v125
	ds_read_b128 v[136:139], v125 offset:1024
	ds_read_b128 v[148:151], v125 offset:2048
	ds_read_b128 v[160:163], v125 offset:3072
	ds_read_b128 v[164:167], v214 offset:32768
	ds_read_b128 v[168:171], v214 offset:33792
	ds_read_b128 v[172:175], v214 offset:34816
	ds_read_b128 v[176:179], v214 offset:35840
	ds_read_b128 v[180:183], v214 offset:36864
	ds_read_b128 v[184:187], v214 offset:37888
	ds_read_b128 v[188:191], v214 offset:38912
	ds_read_b128 v[192:195], v214 offset:39936
	s_add_u32 s92, s2, 0x4000
	s_addc_u32 s93, s3, 0
	s_mov_b32 m0, s64
	s_nop 0
	global_load_lds_dwordx4 v210, s[92:93]
	s_add_u32 s92, s2, 0x6000
	s_addc_u32 s93, s3, 0
	s_mov_b32 m0, s65
	s_nop 0
	global_load_lds_dwordx4 v210, s[92:93]
	s_waitcnt vmcnt(8)
	s_waitcnt lgkmcnt(0)
	s_barrier
	s_setprio 1
	s_waitcnt lgkmcnt(7)
	v_mfma_f32_16x16x32_bf16 v[156:159], v[72:75], v[164:167], v[156:159]
	v_mfma_f32_16x16x32_bf16 v[152:155], v[96:99], v[164:167], v[152:155]
	s_waitcnt lgkmcnt(5)
	v_mfma_f32_16x16x32_bf16 v[130:133], v[72:75], v[172:175], v[132:135]
	v_mfma_f32_16x16x32_bf16 v[126:129], v[96:99], v[172:175], v[126:129]
	s_waitcnt lgkmcnt(3)
	v_mfma_f32_16x16x32_bf16 v[104:107], v[72:75], v[180:183], v[104:107]
	v_mfma_f32_16x16x32_bf16 v[100:103], v[96:99], v[180:183], v[100:103]
	s_waitcnt lgkmcnt(1)
	v_mfma_f32_16x16x32_bf16 v[80:83], v[72:75], v[188:191], v[80:83]
	v_mfma_f32_16x16x32_bf16 v[76:79], v[96:99], v[188:191], v[76:79]
	v_mfma_f32_16x16x32_bf16 v[156:159], v[84:87], v[168:171], v[156:159]
	v_mfma_f32_16x16x32_bf16 v[152:155], v[108:111], v[168:171], v[152:155]
	v_mfma_f32_16x16x32_bf16 v[132:135], v[84:87], v[176:179], v[130:133]
	v_mfma_f32_16x16x32_bf16 v[128:131], v[108:111], v[176:179], v[126:129]
	v_mfma_f32_16x16x32_bf16 v[104:107], v[84:87], v[184:187], v[104:107]
	v_mfma_f32_16x16x32_bf16 v[100:103], v[108:111], v[184:187], v[100:103]
	s_waitcnt lgkmcnt(0)
	v_mfma_f32_16x16x32_bf16 v[80:83], v[84:87], v[192:195], v[80:83]
	v_mfma_f32_16x16x32_bf16 v[76:79], v[108:111], v[192:195], v[76:79]
	s_setprio 0
	s_setprio 1
	s_waitcnt lgkmcnt(0)
	v_mfma_f32_16x16x32_bf16 v[144:147], v[112:115], v[164:167], v[144:147]
	v_mfma_f32_16x16x32_bf16 v[144:147], v[136:139], v[168:171], v[144:147]
	v_mfma_f32_16x16x32_bf16 v[120:123], v[136:139], v[176:179], v[120:123]
	v_mfma_f32_16x16x32_bf16 v[120:123], v[112:115], v[172:175], v[120:123]
	v_mfma_f32_16x16x32_bf16 v[92:95], v[112:115], v[180:183], v[92:95]
	v_mfma_f32_16x16x32_bf16 v[92:95], v[136:139], v[184:187], v[92:95]
	v_mfma_f32_16x16x32_bf16 v[68:71], v[136:139], v[192:195], v[68:71]
	v_mfma_f32_16x16x32_bf16 v[68:71], v[112:115], v[188:191], v[68:71]
	v_mfma_f32_16x16x32_bf16 v[64:67], v[148:151], v[188:191], v[64:67]
	v_mfma_f32_16x16x32_bf16 v[64:67], v[160:163], v[192:195], v[64:67]
	v_mfma_f32_16x16x32_bf16 v[88:91], v[160:163], v[184:187], v[88:91]
	v_mfma_f32_16x16x32_bf16 v[88:91], v[148:151], v[180:183], v[88:91]
	v_mfma_f32_16x16x32_bf16 v[116:119], v[148:151], v[172:175], v[116:119]
	v_mfma_f32_16x16x32_bf16 v[116:119], v[160:163], v[176:179], v[116:119]
	v_mfma_f32_16x16x32_bf16 v[140:143], v[160:163], v[168:171], v[140:143]
	v_mfma_f32_16x16x32_bf16 v[140:143], v[148:151], v[164:167], v[140:143]
	s_setprio 0
	s_barrier
	ds_read_b128 v[164:167], v214 offset:49152
	ds_read_b128 v[168:171], v214 offset:50176
	ds_read_b128 v[172:175], v214 offset:51200
	ds_read_b128 v[176:179], v214 offset:52224
	ds_read_b128 v[180:183], v214 offset:53248
	ds_read_b128 v[184:187], v214 offset:54272
	ds_read_b128 v[188:191], v214 offset:55296
	ds_read_b128 v[192:195], v214 offset:56320
	s_mov_b32 m0, s69
	s_nop 0
	global_load_lds_dwordx4 v210, s[52:53]
	s_add_u32 s52, s58, 0xa000
	s_addc_u32 s53, s59, 0
	s_mov_b32 m0, s70
	s_nop 0
	global_load_lds_dwordx4 v210, s[52:53]
	s_add_u32 s52, s58, 0xc000
	s_addc_u32 s53, s59, 0
	s_mov_b32 m0, s73
	s_nop 0
	global_load_lds_dwordx4 v210, s[52:53]
	s_add_u32 s52, s58, 0xe000
	s_addc_u32 s53, s59, 0
	s_mov_b32 m0, s74
	s_nop 0
	global_load_lds_dwordx4 v210, s[52:53]
	s_add_u32 s2, s2, 0xa000
	s_mov_b32 m0, s71
	s_nop 0
	global_load_lds_dwordx4 v210, s[56:57]
	s_addc_u32 s3, s3, 0
	s_mov_b32 m0, s72
	s_nop 0
	global_load_lds_dwordx4 v210, s[2:3]
	s_waitcnt vmcnt(8)
	s_waitcnt lgkmcnt(0)
	s_barrier
	s_setprio 1
	s_waitcnt lgkmcnt(7)
	s_waitcnt lgkmcnt(0)
	v_mfma_f32_16x16x32_bf16 v[60:63], v[72:75], v[164:167], v[60:63]
	v_mfma_f32_16x16x32_bf16 v[60:63], v[84:87], v[168:171], v[60:63]
	v_mfma_f32_16x16x32_bf16 v[44:47], v[84:87], v[176:179], v[44:47]
	v_mfma_f32_16x16x32_bf16 v[44:47], v[72:75], v[172:175], v[44:47]
	v_mfma_f32_16x16x32_bf16 v[28:31], v[72:75], v[180:183], v[28:31]
	v_mfma_f32_16x16x32_bf16 v[28:31], v[84:87], v[184:187], v[28:31]
	v_mfma_f32_16x16x32_bf16 v[12:15], v[84:87], v[192:195], v[12:15]
	v_mfma_f32_16x16x32_bf16 v[12:15], v[72:75], v[188:191], v[12:15]
	v_mfma_f32_16x16x32_bf16 v[8:11], v[96:99], v[188:191], v[8:11]
	v_mfma_f32_16x16x32_bf16 v[8:11], v[108:111], v[192:195], v[8:11]
	v_mfma_f32_16x16x32_bf16 v[24:27], v[108:111], v[184:187], v[24:27]
	v_mfma_f32_16x16x32_bf16 v[24:27], v[96:99], v[180:183], v[24:27]
	v_mfma_f32_16x16x32_bf16 v[40:43], v[96:99], v[172:175], v[40:43]
	v_mfma_f32_16x16x32_bf16 v[40:43], v[108:111], v[176:179], v[40:43]
	v_mfma_f32_16x16x32_bf16 v[56:59], v[108:111], v[168:171], v[56:59]
	v_mfma_f32_16x16x32_bf16 v[56:59], v[96:99], v[164:167], v[56:59]
	s_setprio 0
	s_setprio 1
	s_waitcnt lgkmcnt(0)
	v_mfma_f32_16x16x32_bf16 v[52:55], v[112:115], v[164:167], v[52:55]
	v_mfma_f32_16x16x32_bf16 v[52:55], v[136:139], v[168:171], v[52:55]
	v_mfma_f32_16x16x32_bf16 v[36:39], v[136:139], v[176:179], v[36:39]
	v_mfma_f32_16x16x32_bf16 v[36:39], v[112:115], v[172:175], v[36:39]
	v_mfma_f32_16x16x32_bf16 v[20:23], v[112:115], v[180:183], v[20:23]
	v_mfma_f32_16x16x32_bf16 v[20:23], v[136:139], v[184:187], v[20:23]
	v_mfma_f32_16x16x32_bf16 v[4:7], v[136:139], v[192:195], v[4:7]
	v_mfma_f32_16x16x32_bf16 v[4:7], v[112:115], v[188:191], v[4:7]
	v_mfma_f32_16x16x32_bf16 v[0:3], v[148:151], v[188:191], v[0:3]
	v_mfma_f32_16x16x32_bf16 v[0:3], v[160:163], v[192:195], v[0:3]
	v_mfma_f32_16x16x32_bf16 v[16:19], v[160:163], v[184:187], v[16:19]
	v_mfma_f32_16x16x32_bf16 v[16:19], v[148:151], v[180:183], v[16:19]
	v_mfma_f32_16x16x32_bf16 v[32:35], v[148:151], v[172:175], v[32:35]
	v_mfma_f32_16x16x32_bf16 v[32:35], v[160:163], v[176:179], v[32:35]
	v_mfma_f32_16x16x32_bf16 v[48:51], v[160:163], v[168:171], v[48:51]
	v_mfma_f32_16x16x32_bf16 v[48:51], v[148:151], v[164:167], v[48:51]
	s_setprio 0
	s_barrier
	s_add_i32 s90, s90, 2
	s_add_u32 s54, s54, 0x10000
	s_addc_u32 s55, s55, 0
	s_add_u32 s88, s88, 0x10000
	s_addc_u32 s89, s89, 0
	s_cmp_gt_u32 s90, 61
	s_cbranch_scc0 .LBB0_1406
	s_and_b64 vcc, exec, s[12:13]
	s_cbranch_vccz .LBB0_1409
	s_barrier

.LBB0_1505:
	ds_read_b128 v[128:131], v156
	ds_read_b128 v[132:135], v156 offset:1024
	ds_read_b128 v[136:139], v156 offset:2048
	ds_read_b128 v[140:143], v156 offset:3072
	ds_read_b128 v[146:149], v157
	ds_read_b128 v[162:165], v157 offset:1024
	ds_read_b128 v[166:169], v157 offset:2048
	ds_read_b128 v[170:173], v157 offset:3072
	s_add_u32 s2, s52, 0x10000
	s_addc_u32 s3, s53, 0
	s_cmp_eq_u32 s96, 60
	s_cselect_b32 s58, s92, s2
	s_cselect_b32 s59, s45, s3
	s_cselect_b32 s64, s93, s54
	s_cselect_b32 s65, s43, s55
	s_add_u32 s60, s58, 0x8000
	s_addc_u32 s61, s59, 0
	ds_read_b128 v[174:177], v158
	ds_read_b128 v[178:181], v158 offset:1024
	ds_read_b128 v[182:185], v158 offset:2048
	ds_read_b128 v[186:189], v158 offset:3072
	ds_read_b128 v[190:193], v158 offset:4096
	ds_read_b128 v[194:197], v158 offset:5120
	ds_read_b128 v[198:201], v158 offset:6144
	ds_read_b128 v[202:205], v158 offset:7168
	s_add_u32 s12, s52, 0xc000
	s_addc_u32 s13, s53, 0
	s_mov_b32 m0, s81
	s_nop 0
	global_load_lds_dwordx4 v154, s[12:13]
	s_add_u32 s12, s52, 0xe000
	s_addc_u32 s13, s53, 0
	s_mov_b32 m0, s82
	s_nop 0
	global_load_lds_dwordx4 v154, s[12:13]
	s_waitcnt vmcnt(8)
	s_waitcnt lgkmcnt(0)
	s_add_u32 s52, s64, 0x8000
	s_addc_u32 s53, s65, 0
	s_barrier
	s_setprio 1
	s_waitcnt lgkmcnt(7)
	s_waitcnt lgkmcnt(0)
	v_mfma_f32_16x16x32_bf16 v[116:119], v[128:131], v[174:177], v[116:119]
	v_mfma_f32_16x16x32_bf16 v[116:119], v[132:135], v[178:181], v[116:119]
	v_mfma_f32_16x16x32_bf16 v[100:103], v[132:135], v[186:189], v[100:103]
	v_mfma_f32_16x16x32_bf16 v[100:103], v[128:131], v[182:185], v[100:103]
	v_mfma_f32_16x16x32_bf16 v[92:95], v[128:131], v[190:193], v[92:95]
	v_mfma_f32_16x16x32_bf16 v[92:95], v[132:135], v[194:197], v[92:95]
	v_mfma_f32_16x16x32_bf16 v[76:79], v[132:135], v[202:205], v[76:79]
	v_mfma_f32_16x16x32_bf16 v[76:79], v[128:131], v[198:201], v[76:79]
	v_mfma_f32_16x16x32_bf16 v[72:75], v[136:139], v[198:201], v[72:75]
	v_mfma_f32_16x16x32_bf16 v[72:75], v[140:143], v[202:205], v[72:75]
	v_mfma_f32_16x16x32_bf16 v[88:91], v[140:143], v[194:197], v[88:91]
	v_mfma_f32_16x16x32_bf16 v[88:91], v[136:139], v[190:193], v[88:91]
	v_mfma_f32_16x16x32_bf16 v[96:99], v[136:139], v[182:185], v[96:99]
	v_mfma_f32_16x16x32_bf16 v[96:99], v[140:143], v[186:189], v[96:99]
	v_mfma_f32_16x16x32_bf16 v[112:115], v[140:143], v[178:181], v[112:115]
	v_mfma_f32_16x16x32_bf16 v[112:115], v[136:139], v[174:177], v[112:115]
	s_setprio 0
	s_setprio 1
	s_waitcnt lgkmcnt(0)
	v_mfma_f32_16x16x32_bf16 v[124:127], v[146:149], v[174:177], v[124:127]
	v_mfma_f32_16x16x32_bf16 v[124:127], v[162:165], v[178:181], v[124:127]
	v_mfma_f32_16x16x32_bf16 v[108:111], v[162:165], v[186:189], v[108:111]
	v_mfma_f32_16x16x32_bf16 v[108:111], v[146:149], v[182:185], v[108:111]
	v_mfma_f32_16x16x32_bf16 v[84:87], v[146:149], v[190:193], v[84:87]
	v_mfma_f32_16x16x32_bf16 v[84:87], v[162:165], v[194:197], v[84:87]
	v_mfma_f32_16x16x32_bf16 v[68:71], v[162:165], v[202:205], v[68:71]
	v_mfma_f32_16x16x32_bf16 v[68:71], v[146:149], v[198:201], v[68:71]
	v_mfma_f32_16x16x32_bf16 v[64:67], v[166:169], v[198:201], v[64:67]
	v_mfma_f32_16x16x32_bf16 v[64:67], v[170:173], v[202:205], v[64:67]
	v_mfma_f32_16x16x32_bf16 v[80:83], v[170:173], v[194:197], v[80:83]
	v_mfma_f32_16x16x32_bf16 v[80:83], v[166:169], v[190:193], v[80:83]
	v_mfma_f32_16x16x32_bf16 v[104:107], v[166:169], v[182:185], v[104:107]
	v_mfma_f32_16x16x32_bf16 v[104:107], v[170:173], v[186:189], v[104:107]
	v_mfma_f32_16x16x32_bf16 v[120:123], v[170:173], v[178:181], v[120:123]
	v_mfma_f32_16x16x32_bf16 v[120:123], v[166:169], v[174:177], v[120:123]
	s_setprio 0
	s_barrier
	s_add_u32 s12, s64, 0x2000
	ds_read_b128 v[174:177], v158 offset:16384
	ds_read_b128 v[178:181], v158 offset:17408
	ds_read_b128 v[182:185], v158 offset:18432
	ds_read_b128 v[186:189], v158 offset:19456
	ds_read_b128 v[190:193], v158 offset:20480
	ds_read_b128 v[194:197], v158 offset:21504
	ds_read_b128 v[198:201], v158 offset:22528
	ds_read_b128 v[202:205], v158 offset:23552
	s_mov_b32 m0, s57
	s_nop 0
	global_load_lds_dwordx4 v154, s[64:65]
	s_addc_u32 s13, s65, 0
	s_mov_b32 m0, s67
	s_nop 0
	global_load_lds_dwordx4 v154, s[12:13]
	s_add_u32 s12, s64, 0x4000
	s_addc_u32 s13, s65, 0
	s_mov_b32 m0, s68
	s_nop 0
	global_load_lds_dwordx4 v154, s[12:13]
	s_add_u32 s12, s64, 0x6000
	s_addc_u32 s13, s65, 0
	s_mov_b32 m0, s69
	s_nop 0
	global_load_lds_dwordx4 v154, s[12:13]
	s_add_u32 s12, s58, 0x2000
	s_mov_b32 m0, s66
	s_nop 0
	global_load_lds_dwordx4 v154, s[58:59]
	s_addc_u32 s13, s59, 0
	s_mov_b32 m0, s70
	s_nop 0
	global_load_lds_dwordx4 v154, s[12:13]
	s_waitcnt vmcnt(8)
	s_waitcnt lgkmcnt(0)
	s_barrier
	s_setprio 1
	s_waitcnt lgkmcnt(7)
	s_waitcnt lgkmcnt(0)
	v_mfma_f32_16x16x32_bf16 v[60:63], v[128:131], v[174:177], v[60:63]
	v_mfma_f32_16x16x32_bf16 v[60:63], v[132:135], v[178:181], v[60:63]
	v_mfma_f32_16x16x32_bf16 v[44:47], v[132:135], v[186:189], v[44:47]
	v_mfma_f32_16x16x32_bf16 v[44:47], v[128:131], v[182:185], v[44:47]
	v_mfma_f32_16x16x32_bf16 v[28:31], v[128:131], v[190:193], v[28:31]
	v_mfma_f32_16x16x32_bf16 v[28:31], v[132:135], v[194:197], v[28:31]
	v_mfma_f32_16x16x32_bf16 v[12:15], v[132:135], v[202:205], v[12:15]
	v_mfma_f32_16x16x32_bf16 v[12:15], v[128:131], v[198:201], v[12:15]
	v_mfma_f32_16x16x32_bf16 v[8:11], v[136:139], v[198:201], v[8:11]
	v_mfma_f32_16x16x32_bf16 v[8:11], v[140:143], v[202:205], v[8:11]
	v_mfma_f32_16x16x32_bf16 v[24:27], v[140:143], v[194:197], v[24:27]
	v_mfma_f32_16x16x32_bf16 v[24:27], v[136:139], v[190:193], v[24:27]
	v_mfma_f32_16x16x32_bf16 v[40:43], v[136:139], v[182:185], v[40:43]
	v_mfma_f32_16x16x32_bf16 v[40:43], v[140:143], v[186:189], v[40:43]
	v_mfma_f32_16x16x32_bf16 v[56:59], v[140:143], v[178:181], v[56:59]
	v_mfma_f32_16x16x32_bf16 v[56:59], v[136:139], v[174:177], v[56:59]
	s_setprio 0
	s_setprio 1
	s_waitcnt lgkmcnt(0)
	v_mfma_f32_16x16x32_bf16 v[52:55], v[146:149], v[174:177], v[52:55]
	v_mfma_f32_16x16x32_bf16 v[52:55], v[162:165], v[178:181], v[52:55]
	v_mfma_f32_16x16x32_bf16 v[36:39], v[162:165], v[186:189], v[36:39]
	v_mfma_f32_16x16x32_bf16 v[36:39], v[146:149], v[182:185], v[36:39]
	v_mfma_f32_16x16x32_bf16 v[20:23], v[146:149], v[190:193], v[20:23]
	v_mfma_f32_16x16x32_bf16 v[20:23], v[162:165], v[194:197], v[20:23]
	v_mfma_f32_16x16x32_bf16 v[4:7], v[162:165], v[202:205], v[4:7]
	v_mfma_f32_16x16x32_bf16 v[4:7], v[146:149], v[198:201], v[4:7]
	v_mfma_f32_16x16x32_bf16 v[0:3], v[166:169], v[198:201], v[0:3]
	v_mfma_f32_16x16x32_bf16 v[0:3], v[170:173], v[202:205], v[0:3]
	v_mfma_f32_16x16x32_bf16 v[16:19], v[170:173], v[194:197], v[16:19]
	v_mfma_f32_16x16x32_bf16 v[16:19], v[166:169], v[190:193], v[16:19]
	v_mfma_f32_16x16x32_bf16 v[32:35], v[166:169], v[182:185], v[32:35]
	v_mfma_f32_16x16x32_bf16 v[32:35], v[170:173], v[186:189], v[32:35]
	v_mfma_f32_16x16x32_bf16 v[48:51], v[170:173], v[178:181], v[48:51]
	v_mfma_f32_16x16x32_bf16 v[48:51], v[166:169], v[174:177], v[48:51]
	s_setprio 0
	s_barrier
	ds_read_b128 v[128:131], v144
	ds_read_b128 v[132:135], v144 offset:1024
	ds_read_b128 v[136:139], v144 offset:2048
	ds_read_b128 v[140:143], v144 offset:3072
	ds_read_b128 v[146:149], v150
	ds_read_b128 v[162:165], v150 offset:1024
	ds_read_b128 v[166:169], v150 offset:2048
	ds_read_b128 v[170:173], v150 offset:3072
	ds_read_b128 v[174:177], v158 offset:32768
	ds_read_b128 v[178:181], v158 offset:33792
	ds_read_b128 v[182:185], v158 offset:34816
	ds_read_b128 v[186:189], v158 offset:35840
	ds_read_b128 v[190:193], v158 offset:36864
	ds_read_b128 v[194:197], v158 offset:37888
	ds_read_b128 v[198:201], v158 offset:38912
	ds_read_b128 v[202:205], v158 offset:39936
	s_add_u32 s12, s58, 0x4000
	s_addc_u32 s13, s59, 0
	s_mov_b32 m0, s71
	s_nop 0
	global_load_lds_dwordx4 v154, s[12:13]
	s_add_u32 s12, s58, 0x6000
	s_addc_u32 s13, s59, 0
	s_mov_b32 m0, s72
	s_nop 0
	global_load_lds_dwordx4 v154, s[12:13]
	s_waitcnt vmcnt(8)
	s_waitcnt lgkmcnt(0)
	s_barrier
	s_setprio 1
	s_waitcnt lgkmcnt(7)
	s_waitcnt lgkmcnt(0)
	v_mfma_f32_16x16x32_bf16 v[116:119], v[128:131], v[174:177], v[116:119]
	v_mfma_f32_16x16x32_bf16 v[116:119], v[132:135], v[178:181], v[116:119]
	v_mfma_f32_16x16x32_bf16 v[100:103], v[132:135], v[186:189], v[100:103]
	v_mfma_f32_16x16x32_bf16 v[100:103], v[128:131], v[182:185], v[100:103]
	v_mfma_f32_16x16x32_bf16 v[92:95], v[128:131], v[190:193], v[92:95]
	v_mfma_f32_16x16x32_bf16 v[92:95], v[132:135], v[194:197], v[92:95]
	v_mfma_f32_16x16x32_bf16 v[76:79], v[132:135], v[202:205], v[76:79]
	v_mfma_f32_16x16x32_bf16 v[76:79], v[128:131], v[198:201], v[76:79]
	v_mfma_f32_16x16x32_bf16 v[72:75], v[136:139], v[198:201], v[72:75]
	v_mfma_f32_16x16x32_bf16 v[72:75], v[140:143], v[202:205], v[72:75]
	v_mfma_f32_16x16x32_bf16 v[88:91], v[140:143], v[194:197], v[88:91]
	v_mfma_f32_16x16x32_bf16 v[88:91], v[136:139], v[190:193], v[88:91]
	v_mfma_f32_16x16x32_bf16 v[96:99], v[136:139], v[182:185], v[96:99]
	v_mfma_f32_16x16x32_bf16 v[96:99], v[140:143], v[186:189], v[96:99]
	v_mfma_f32_16x16x32_bf16 v[112:115], v[140:143], v[178:181], v[112:115]
	v_mfma_f32_16x16x32_bf16 v[112:115], v[136:139], v[174:177], v[112:115]
	s_setprio 0
	s_setprio 1
	s_waitcnt lgkmcnt(0)
	v_mfma_f32_16x16x32_bf16 v[124:127], v[146:149], v[174:177], v[124:127]
	v_mfma_f32_16x16x32_bf16 v[124:127], v[162:165], v[178:181], v[124:127]
	v_mfma_f32_16x16x32_bf16 v[108:111], v[162:165], v[186:189], v[108:111]
	v_mfma_f32_16x16x32_bf16 v[108:111], v[146:149], v[182:185], v[108:111]
	v_mfma_f32_16x16x32_bf16 v[84:87], v[146:149], v[190:193], v[84:87]
	v_mfma_f32_16x16x32_bf16 v[84:87], v[162:165], v[194:197], v[84:87]
	v_mfma_f32_16x16x32_bf16 v[68:71], v[162:165], v[202:205], v[68:71]
	v_mfma_f32_16x16x32_bf16 v[68:71], v[146:149], v[198:201], v[68:71]
	v_mfma_f32_16x16x32_bf16 v[64:67], v[166:169], v[198:201], v[64:67]
	v_mfma_f32_16x16x32_bf16 v[64:67], v[170:173], v[202:205], v[64:67]
	v_mfma_f32_16x16x32_bf16 v[80:83], v[170:173], v[194:197], v[80:83]
	v_mfma_f32_16x16x32_bf16 v[80:83], v[166:169], v[190:193], v[80:83]
	v_mfma_f32_16x16x32_bf16 v[104:107], v[166:169], v[182:185], v[104:107]
	v_mfma_f32_16x16x32_bf16 v[104:107], v[170:173], v[186:189], v[104:107]
	v_mfma_f32_16x16x32_bf16 v[120:123], v[170:173], v[178:181], v[120:123]
	v_mfma_f32_16x16x32_bf16 v[120:123], v[166:169], v[174:177], v[120:123]
	s_setprio 0
	s_barrier
	s_add_u32 s12, s64, 0xa000
	ds_read_b128 v[174:177], v158 offset:49152
	ds_read_b128 v[178:181], v158 offset:50176
	ds_read_b128 v[182:185], v158 offset:51200
	ds_read_b128 v[186:189], v158 offset:52224
	ds_read_b128 v[190:193], v158 offset:53248
	ds_read_b128 v[194:197], v158 offset:54272
	ds_read_b128 v[198:201], v158 offset:55296
	ds_read_b128 v[202:205], v158 offset:56320
	s_mov_b32 m0, s75
	s_nop 0
	global_load_lds_dwordx4 v154, s[52:53]
	s_addc_u32 s13, s65, 0
	s_mov_b32 m0, s76
	s_nop 0
	global_load_lds_dwordx4 v154, s[12:13]
	s_add_u32 s12, s64, 0xc000
	s_addc_u32 s13, s65, 0
	s_mov_b32 m0, s79
	s_nop 0
	global_load_lds_dwordx4 v154, s[12:13]
	s_add_u32 s12, s64, 0xe000
	s_addc_u32 s13, s65, 0
	s_mov_b32 m0, s80
	s_nop 0
	global_load_lds_dwordx4 v154, s[12:13]
	s_add_u32 s12, s58, 0xa000
	s_mov_b32 m0, s77
	s_nop 0
	global_load_lds_dwordx4 v154, s[60:61]
	s_addc_u32 s13, s59, 0
	s_mov_b32 m0, s78
	s_nop 0
	global_load_lds_dwordx4 v154, s[12:13]
	s_waitcnt vmcnt(8)
	s_waitcnt lgkmcnt(0)
	s_barrier
	s_setprio 1
	s_waitcnt lgkmcnt(7)
	s_waitcnt lgkmcnt(0)
	v_mfma_f32_16x16x32_bf16 v[60:63], v[128:131], v[174:177], v[60:63]
	v_mfma_f32_16x16x32_bf16 v[60:63], v[132:135], v[178:181], v[60:63]
	v_mfma_f32_16x16x32_bf16 v[44:47], v[132:135], v[186:189], v[44:47]
	v_mfma_f32_16x16x32_bf16 v[44:47], v[128:131], v[182:185], v[44:47]
	v_mfma_f32_16x16x32_bf16 v[28:31], v[128:131], v[190:193], v[28:31]
	v_mfma_f32_16x16x32_bf16 v[28:31], v[132:135], v[194:197], v[28:31]
	v_mfma_f32_16x16x32_bf16 v[12:15], v[132:135], v[202:205], v[12:15]
	v_mfma_f32_16x16x32_bf16 v[12:15], v[128:131], v[198:201], v[12:15]
	v_mfma_f32_16x16x32_bf16 v[8:11], v[136:139], v[198:201], v[8:11]
	v_mfma_f32_16x16x32_bf16 v[8:11], v[140:143], v[202:205], v[8:11]
	v_mfma_f32_16x16x32_bf16 v[24:27], v[140:143], v[194:197], v[24:27]
	v_mfma_f32_16x16x32_bf16 v[24:27], v[136:139], v[190:193], v[24:27]
	v_mfma_f32_16x16x32_bf16 v[40:43], v[136:139], v[182:185], v[40:43]
	v_mfma_f32_16x16x32_bf16 v[40:43], v[140:143], v[186:189], v[40:43]
	v_mfma_f32_16x16x32_bf16 v[56:59], v[140:143], v[178:181], v[56:59]
	v_mfma_f32_16x16x32_bf16 v[56:59], v[136:139], v[174:177], v[56:59]
	s_setprio 0
	s_setprio 1
	s_waitcnt lgkmcnt(0)
	v_mfma_f32_16x16x32_bf16 v[52:55], v[146:149], v[174:177], v[52:55]
	v_mfma_f32_16x16x32_bf16 v[52:55], v[162:165], v[178:181], v[52:55]
	v_mfma_f32_16x16x32_bf16 v[36:39], v[162:165], v[186:189], v[36:39]
	v_mfma_f32_16x16x32_bf16 v[36:39], v[146:149], v[182:185], v[36:39]
	v_mfma_f32_16x16x32_bf16 v[20:23], v[146:149], v[190:193], v[20:23]
	v_mfma_f32_16x16x32_bf16 v[20:23], v[162:165], v[194:197], v[20:23]
	v_mfma_f32_16x16x32_bf16 v[4:7], v[162:165], v[202:205], v[4:7]
	v_mfma_f32_16x16x32_bf16 v[4:7], v[146:149], v[198:201], v[4:7]
	v_mfma_f32_16x16x32_bf16 v[0:3], v[166:169], v[198:201], v[0:3]
	v_mfma_f32_16x16x32_bf16 v[0:3], v[170:173], v[202:205], v[0:3]
	v_mfma_f32_16x16x32_bf16 v[16:19], v[170:173], v[194:197], v[16:19]
	v_mfma_f32_16x16x32_bf16 v[16:19], v[166:169], v[190:193], v[16:19]
	v_mfma_f32_16x16x32_bf16 v[32:35], v[166:169], v[182:185], v[32:35]
	v_mfma_f32_16x16x32_bf16 v[32:35], v[170:173], v[186:189], v[32:35]
	v_mfma_f32_16x16x32_bf16 v[48:51], v[170:173], v[178:181], v[48:51]
	v_mfma_f32_16x16x32_bf16 v[48:51], v[166:169], v[174:177], v[48:51]
	s_setprio 0
	s_barrier
	s_add_i32 s96, s96, 2
	s_add_u32 s54, s54, 0x10000
	s_addc_u32 s55, s55, 0
	s_cmp_gt_u32 s96, 61
	s_mov_b64 s[52:53], s[2:3]
	s_cbranch_scc0 .LBB0_1505
	s_and_b64 vcc, exec, s[40:41]
	s_cbranch_vccz .LBB0_1508
	s_barrier

.LBB0_1539:
	ds_read_b128 v[128:131], v138
	ds_read_b128 v[132:135], v138 offset:1024
	ds_read_b128 v[144:147], v138 offset:2048
	ds_read_b128 v[148:151], v138 offset:3072
	ds_read_b128 v[152:155], v139
	ds_read_b128 v[156:159], v139 offset:1024
	ds_read_b128 v[160:163], v139 offset:2048
	ds_read_b128 v[164:167], v139 offset:3072
	s_add_u32 s2, s52, 0x10000
	s_addc_u32 s3, s53, 0
	s_cmp_eq_u32 s83, 60
	s_cselect_b32 s46, s79, s2
	s_cselect_b32 s47, s39, s3
	s_cselect_b32 s56, s80, s81
	s_cselect_b32 s57, s15, s82
	s_add_u32 s48, s46, 0x8000
	s_addc_u32 s49, s47, 0
	ds_read_b128 v[168:171], v140
	ds_read_b128 v[172:175], v140 offset:1024
	ds_read_b128 v[176:179], v140 offset:2048
	ds_read_b128 v[180:183], v140 offset:3072
	ds_read_b128 v[184:187], v140 offset:4096
	ds_read_b128 v[188:191], v140 offset:5120
	ds_read_b128 v[192:195], v140 offset:6144
	ds_read_b128 v[196:199], v140 offset:7168
	s_add_u32 s88, s52, 0xc000
	s_addc_u32 s89, s53, 0
	s_mov_b32 m0, s74
	s_nop 0
	global_load_lds_dwordx4 v136, s[88:89]
	s_add_u32 s52, s52, 0xe000
	s_addc_u32 s53, s53, 0
	s_mov_b32 m0, s75
	s_nop 0
	global_load_lds_dwordx4 v136, s[52:53]
	s_waitcnt vmcnt(8)
	s_waitcnt lgkmcnt(0)
	s_add_u32 s52, s56, 0x8000
	s_addc_u32 s53, s57, 0
	s_barrier
	s_setprio 1
	s_waitcnt lgkmcnt(7)
	s_waitcnt lgkmcnt(0)
	v_mfma_f32_16x16x32_bf16 v[120:123], v[128:131], v[168:171], v[120:123]
	v_mfma_f32_16x16x32_bf16 v[120:123], v[132:135], v[172:175], v[120:123]
	v_mfma_f32_16x16x32_bf16 v[104:107], v[132:135], v[180:183], v[104:107]
	v_mfma_f32_16x16x32_bf16 v[104:107], v[128:131], v[176:179], v[104:107]
	v_mfma_f32_16x16x32_bf16 v[84:87], v[128:131], v[184:187], v[84:87]
	v_mfma_f32_16x16x32_bf16 v[84:87], v[132:135], v[188:191], v[84:87]
	v_mfma_f32_16x16x32_bf16 v[52:55], v[132:135], v[196:199], v[52:55]
	v_mfma_f32_16x16x32_bf16 v[52:55], v[128:131], v[192:195], v[52:55]
	v_mfma_f32_16x16x32_bf16 v[36:39], v[144:147], v[192:195], v[36:39]
	v_mfma_f32_16x16x32_bf16 v[36:39], v[148:151], v[196:199], v[36:39]
	v_mfma_f32_16x16x32_bf16 v[68:71], v[148:151], v[188:191], v[68:71]
	v_mfma_f32_16x16x32_bf16 v[68:71], v[144:147], v[184:187], v[68:71]
	v_mfma_f32_16x16x32_bf16 v[96:99], v[144:147], v[176:179], v[96:99]
	v_mfma_f32_16x16x32_bf16 v[96:99], v[148:151], v[180:183], v[96:99]
	v_mfma_f32_16x16x32_bf16 v[112:115], v[148:151], v[172:175], v[112:115]
	v_mfma_f32_16x16x32_bf16 v[112:115], v[144:147], v[168:171], v[112:115]
	s_setprio 0
	s_setprio 1
	s_waitcnt lgkmcnt(0)
	v_mfma_f32_16x16x32_bf16 v[124:127], v[152:155], v[168:171], v[124:127]
	v_mfma_f32_16x16x32_bf16 v[124:127], v[156:159], v[172:175], v[124:127]
	v_mfma_f32_16x16x32_bf16 v[108:111], v[156:159], v[180:183], v[108:111]
	v_mfma_f32_16x16x32_bf16 v[108:111], v[152:155], v[176:179], v[108:111]
	v_mfma_f32_16x16x32_bf16 v[88:91], v[152:155], v[184:187], v[88:91]
	v_mfma_f32_16x16x32_bf16 v[88:91], v[156:159], v[188:191], v[88:91]
	v_mfma_f32_16x16x32_bf16 v[56:59], v[156:159], v[196:199], v[56:59]
	v_mfma_f32_16x16x32_bf16 v[56:59], v[152:155], v[192:195], v[56:59]
	v_mfma_f32_16x16x32_bf16 v[40:43], v[160:163], v[192:195], v[40:43]
	v_mfma_f32_16x16x32_bf16 v[40:43], v[164:167], v[196:199], v[40:43]
	v_mfma_f32_16x16x32_bf16 v[72:75], v[164:167], v[188:191], v[72:75]
	v_mfma_f32_16x16x32_bf16 v[72:75], v[160:163], v[184:187], v[72:75]
	v_mfma_f32_16x16x32_bf16 v[100:103], v[160:163], v[176:179], v[100:103]
	v_mfma_f32_16x16x32_bf16 v[100:103], v[164:167], v[180:183], v[100:103]
	v_mfma_f32_16x16x32_bf16 v[116:119], v[164:167], v[172:175], v[116:119]
	v_mfma_f32_16x16x32_bf16 v[116:119], v[160:163], v[168:171], v[116:119]
	s_setprio 0
	s_barrier
	s_add_u32 s88, s56, 0x2000
	ds_read_b128 v[168:171], v140 offset:16384
	ds_read_b128 v[172:175], v140 offset:17408
	ds_read_b128 v[176:179], v140 offset:18432
	ds_read_b128 v[180:183], v140 offset:19456
	ds_read_b128 v[184:187], v140 offset:20480
	ds_read_b128 v[188:191], v140 offset:21504
	ds_read_b128 v[192:195], v140 offset:22528
	ds_read_b128 v[196:199], v140 offset:23552
	s_mov_b32 m0, s41
	s_nop 0
	global_load_lds_dwordx4 v136, s[56:57]
	s_addc_u32 s89, s57, 0
	s_mov_b32 m0, s59
	s_nop 0
	global_load_lds_dwordx4 v136, s[88:89]
	s_add_u32 s88, s56, 0x4000
	s_addc_u32 s89, s57, 0
	s_mov_b32 m0, s60
	s_nop 0
	global_load_lds_dwordx4 v136, s[88:89]
	s_add_u32 s88, s56, 0x6000
	s_addc_u32 s89, s57, 0
	s_mov_b32 m0, s61
	s_nop 0
	global_load_lds_dwordx4 v136, s[88:89]
	s_add_u32 s88, s46, 0x2000
	s_mov_b32 m0, s58
	s_nop 0
	global_load_lds_dwordx4 v136, s[46:47]
	s_addc_u32 s89, s47, 0
	s_mov_b32 m0, s62
	s_nop 0
	global_load_lds_dwordx4 v136, s[88:89]
	s_waitcnt vmcnt(8)
	s_waitcnt lgkmcnt(0)
	s_barrier
	s_setprio 1
	s_waitcnt lgkmcnt(7)
	s_waitcnt lgkmcnt(0)
	v_mfma_f32_16x16x32_bf16 v[92:95], v[128:131], v[168:171], v[92:95]
	v_mfma_f32_16x16x32_bf16 v[92:95], v[132:135], v[172:175], v[92:95]
	v_mfma_f32_16x16x32_bf16 v[60:63], v[132:135], v[180:183], v[60:63]
	v_mfma_f32_16x16x32_bf16 v[60:63], v[128:131], v[176:179], v[60:63]
	v_mfma_f32_16x16x32_bf16 v[28:31], v[128:131], v[184:187], v[28:31]
	v_mfma_f32_16x16x32_bf16 v[28:31], v[132:135], v[188:191], v[28:31]
	v_mfma_f32_16x16x32_bf16 v[12:15], v[132:135], v[196:199], v[12:15]
	v_mfma_f32_16x16x32_bf16 v[12:15], v[128:131], v[192:195], v[12:15]
	v_mfma_f32_16x16x32_bf16 v[8:11], v[144:147], v[192:195], v[8:11]
	v_mfma_f32_16x16x32_bf16 v[8:11], v[148:151], v[196:199], v[8:11]
	v_mfma_f32_16x16x32_bf16 v[24:27], v[148:151], v[188:191], v[24:27]
	v_mfma_f32_16x16x32_bf16 v[24:27], v[144:147], v[184:187], v[24:27]
	v_mfma_f32_16x16x32_bf16 v[48:51], v[144:147], v[176:179], v[48:51]
	v_mfma_f32_16x16x32_bf16 v[48:51], v[148:151], v[180:183], v[48:51]
	v_mfma_f32_16x16x32_bf16 v[80:83], v[148:151], v[172:175], v[80:83]
	v_mfma_f32_16x16x32_bf16 v[80:83], v[144:147], v[168:171], v[80:83]
	s_setprio 0
	s_setprio 1
	s_waitcnt lgkmcnt(0)
	v_mfma_f32_16x16x32_bf16 v[76:79], v[152:155], v[168:171], v[76:79]
	v_mfma_f32_16x16x32_bf16 v[76:79], v[156:159], v[172:175], v[76:79]
	v_mfma_f32_16x16x32_bf16 v[44:47], v[156:159], v[180:183], v[44:47]
	v_mfma_f32_16x16x32_bf16 v[44:47], v[152:155], v[176:179], v[44:47]
	v_mfma_f32_16x16x32_bf16 v[20:23], v[152:155], v[184:187], v[20:23]
	v_mfma_f32_16x16x32_bf16 v[20:23], v[156:159], v[188:191], v[20:23]
	v_mfma_f32_16x16x32_bf16 v[4:7], v[156:159], v[196:199], v[4:7]
	v_mfma_f32_16x16x32_bf16 v[4:7], v[152:155], v[192:195], v[4:7]
	v_mfma_f32_16x16x32_bf16 v[0:3], v[160:163], v[192:195], v[0:3]
	v_mfma_f32_16x16x32_bf16 v[0:3], v[164:167], v[196:199], v[0:3]
	v_mfma_f32_16x16x32_bf16 v[16:19], v[164:167], v[188:191], v[16:19]
	v_mfma_f32_16x16x32_bf16 v[16:19], v[160:163], v[184:187], v[16:19]
	v_mfma_f32_16x16x32_bf16 v[32:35], v[160:163], v[176:179], v[32:35]
	v_mfma_f32_16x16x32_bf16 v[32:35], v[164:167], v[180:183], v[32:35]
	v_mfma_f32_16x16x32_bf16 v[64:67], v[164:167], v[172:175], v[64:67]
	v_mfma_f32_16x16x32_bf16 v[64:67], v[160:163], v[168:171], v[64:67]
	s_setprio 0
	s_barrier
	ds_read_b128 v[128:131], v141
	ds_read_b128 v[132:135], v141 offset:1024
	ds_read_b128 v[144:147], v141 offset:2048
	ds_read_b128 v[148:151], v141 offset:3072
	ds_read_b128 v[152:155], v142
	ds_read_b128 v[156:159], v142 offset:1024
	ds_read_b128 v[160:163], v142 offset:2048
	ds_read_b128 v[164:167], v142 offset:3072
	ds_read_b128 v[168:171], v140 offset:32768
	ds_read_b128 v[172:175], v140 offset:33792
	ds_read_b128 v[176:179], v140 offset:34816
	ds_read_b128 v[180:183], v140 offset:35840
	ds_read_b128 v[184:187], v140 offset:36864
	ds_read_b128 v[188:191], v140 offset:37888
	ds_read_b128 v[192:195], v140 offset:38912
	ds_read_b128 v[196:199], v140 offset:39936
	s_add_u32 s88, s46, 0x4000
	s_addc_u32 s89, s47, 0
	s_mov_b32 m0, s63
	s_nop 0
	global_load_lds_dwordx4 v136, s[88:89]
	s_add_u32 s88, s46, 0x6000
	s_addc_u32 s89, s47, 0
	s_mov_b32 m0, s64
	s_nop 0
	global_load_lds_dwordx4 v136, s[88:89]
	s_waitcnt vmcnt(8)
	s_waitcnt lgkmcnt(0)
	s_barrier
	s_setprio 1
	s_waitcnt lgkmcnt(7)
	s_waitcnt lgkmcnt(0)
	v_mfma_f32_16x16x32_bf16 v[120:123], v[128:131], v[168:171], v[120:123]
	v_mfma_f32_16x16x32_bf16 v[120:123], v[132:135], v[172:175], v[120:123]
	v_mfma_f32_16x16x32_bf16 v[104:107], v[132:135], v[180:183], v[104:107]
	v_mfma_f32_16x16x32_bf16 v[104:107], v[128:131], v[176:179], v[104:107]
	v_mfma_f32_16x16x32_bf16 v[84:87], v[128:131], v[184:187], v[84:87]
	v_mfma_f32_16x16x32_bf16 v[84:87], v[132:135], v[188:191], v[84:87]
	v_mfma_f32_16x16x32_bf16 v[52:55], v[132:135], v[196:199], v[52:55]
	v_mfma_f32_16x16x32_bf16 v[52:55], v[128:131], v[192:195], v[52:55]
	v_mfma_f32_16x16x32_bf16 v[36:39], v[144:147], v[192:195], v[36:39]
	v_mfma_f32_16x16x32_bf16 v[36:39], v[148:151], v[196:199], v[36:39]
	v_mfma_f32_16x16x32_bf16 v[68:71], v[148:151], v[188:191], v[68:71]
	v_mfma_f32_16x16x32_bf16 v[68:71], v[144:147], v[184:187], v[68:71]
	v_mfma_f32_16x16x32_bf16 v[96:99], v[144:147], v[176:179], v[96:99]
	v_mfma_f32_16x16x32_bf16 v[96:99], v[148:151], v[180:183], v[96:99]
	v_mfma_f32_16x16x32_bf16 v[112:115], v[148:151], v[172:175], v[112:115]
	v_mfma_f32_16x16x32_bf16 v[112:115], v[144:147], v[168:171], v[112:115]
	s_setprio 0
	s_setprio 1
	s_waitcnt lgkmcnt(0)
	v_mfma_f32_16x16x32_bf16 v[124:127], v[152:155], v[168:171], v[124:127]
	v_mfma_f32_16x16x32_bf16 v[124:127], v[156:159], v[172:175], v[124:127]
	v_mfma_f32_16x16x32_bf16 v[108:111], v[156:159], v[180:183], v[108:111]
	v_mfma_f32_16x16x32_bf16 v[108:111], v[152:155], v[176:179], v[108:111]
	v_mfma_f32_16x16x32_bf16 v[88:91], v[152:155], v[184:187], v[88:91]
	v_mfma_f32_16x16x32_bf16 v[88:91], v[156:159], v[188:191], v[88:91]
	v_mfma_f32_16x16x32_bf16 v[56:59], v[156:159], v[196:199], v[56:59]
	v_mfma_f32_16x16x32_bf16 v[56:59], v[152:155], v[192:195], v[56:59]
	v_mfma_f32_16x16x32_bf16 v[40:43], v[160:163], v[192:195], v[40:43]
	v_mfma_f32_16x16x32_bf16 v[40:43], v[164:167], v[196:199], v[40:43]
	v_mfma_f32_16x16x32_bf16 v[72:75], v[164:167], v[188:191], v[72:75]
	v_mfma_f32_16x16x32_bf16 v[72:75], v[160:163], v[184:187], v[72:75]
	v_mfma_f32_16x16x32_bf16 v[100:103], v[160:163], v[176:179], v[100:103]
	v_mfma_f32_16x16x32_bf16 v[100:103], v[164:167], v[180:183], v[100:103]
	v_mfma_f32_16x16x32_bf16 v[116:119], v[164:167], v[172:175], v[116:119]
	v_mfma_f32_16x16x32_bf16 v[116:119], v[160:163], v[168:171], v[116:119]
	s_setprio 0
	s_barrier
	ds_read_b128 v[168:171], v140 offset:49152
	ds_read_b128 v[172:175], v140 offset:50176
	ds_read_b128 v[176:179], v140 offset:51200
	ds_read_b128 v[180:183], v140 offset:52224
	ds_read_b128 v[184:187], v140 offset:53248
	ds_read_b128 v[188:191], v140 offset:54272
	ds_read_b128 v[192:195], v140 offset:55296
	ds_read_b128 v[196:199], v140 offset:56320
	s_mov_b32 m0, s68
	s_nop 0
	global_load_lds_dwordx4 v136, s[52:53]
	s_add_u32 s52, s56, 0xa000
	s_addc_u32 s53, s57, 0
	s_mov_b32 m0, s69
	s_nop 0
	global_load_lds_dwordx4 v136, s[52:53]
	s_add_u32 s52, s56, 0xc000
	s_addc_u32 s53, s57, 0
	s_mov_b32 m0, s72
	s_nop 0
	global_load_lds_dwordx4 v136, s[52:53]
	s_add_u32 s52, s56, 0xe000
	s_addc_u32 s53, s57, 0
	s_mov_b32 m0, s73
	s_nop 0
	global_load_lds_dwordx4 v136, s[52:53]
	s_add_u32 s46, s46, 0xa000
	s_mov_b32 m0, s70
	s_nop 0
	global_load_lds_dwordx4 v136, s[48:49]
	s_addc_u32 s47, s47, 0
	s_mov_b32 m0, s71
	s_nop 0
	global_load_lds_dwordx4 v136, s[46:47]
	s_waitcnt vmcnt(8)
	s_waitcnt lgkmcnt(0)
	s_barrier
	s_setprio 1
	s_waitcnt lgkmcnt(7)
	s_waitcnt lgkmcnt(0)
	v_mfma_f32_16x16x32_bf16 v[92:95], v[128:131], v[168:171], v[92:95]
	v_mfma_f32_16x16x32_bf16 v[92:95], v[132:135], v[172:175], v[92:95]
	v_mfma_f32_16x16x32_bf16 v[60:63], v[132:135], v[180:183], v[60:63]
	v_mfma_f32_16x16x32_bf16 v[60:63], v[128:131], v[176:179], v[60:63]
	v_mfma_f32_16x16x32_bf16 v[28:31], v[128:131], v[184:187], v[28:31]
	v_mfma_f32_16x16x32_bf16 v[28:31], v[132:135], v[188:191], v[28:31]
	v_mfma_f32_16x16x32_bf16 v[12:15], v[132:135], v[196:199], v[12:15]
	v_mfma_f32_16x16x32_bf16 v[12:15], v[128:131], v[192:195], v[12:15]
	v_mfma_f32_16x16x32_bf16 v[8:11], v[144:147], v[192:195], v[8:11]
	v_mfma_f32_16x16x32_bf16 v[8:11], v[148:151], v[196:199], v[8:11]
	v_mfma_f32_16x16x32_bf16 v[24:27], v[148:151], v[188:191], v[24:27]
	v_mfma_f32_16x16x32_bf16 v[24:27], v[144:147], v[184:187], v[24:27]
	v_mfma_f32_16x16x32_bf16 v[48:51], v[144:147], v[176:179], v[48:51]
	v_mfma_f32_16x16x32_bf16 v[48:51], v[148:151], v[180:183], v[48:51]
	v_mfma_f32_16x16x32_bf16 v[80:83], v[148:151], v[172:175], v[80:83]
	v_mfma_f32_16x16x32_bf16 v[80:83], v[144:147], v[168:171], v[80:83]
	s_setprio 0
	s_setprio 1
	s_waitcnt lgkmcnt(0)
	v_mfma_f32_16x16x32_bf16 v[76:79], v[152:155], v[168:171], v[76:79]
	v_mfma_f32_16x16x32_bf16 v[76:79], v[156:159], v[172:175], v[76:79]
	v_mfma_f32_16x16x32_bf16 v[44:47], v[156:159], v[180:183], v[44:47]
	v_mfma_f32_16x16x32_bf16 v[44:47], v[152:155], v[176:179], v[44:47]
	v_mfma_f32_16x16x32_bf16 v[20:23], v[152:155], v[184:187], v[20:23]
	v_mfma_f32_16x16x32_bf16 v[20:23], v[156:159], v[188:191], v[20:23]
	v_mfma_f32_16x16x32_bf16 v[4:7], v[156:159], v[196:199], v[4:7]
	v_mfma_f32_16x16x32_bf16 v[4:7], v[152:155], v[192:195], v[4:7]
	v_mfma_f32_16x16x32_bf16 v[0:3], v[160:163], v[192:195], v[0:3]
	v_mfma_f32_16x16x32_bf16 v[0:3], v[164:167], v[196:199], v[0:3]
	v_mfma_f32_16x16x32_bf16 v[16:19], v[164:167], v[188:191], v[16:19]
	v_mfma_f32_16x16x32_bf16 v[16:19], v[160:163], v[184:187], v[16:19]
	v_mfma_f32_16x16x32_bf16 v[32:35], v[160:163], v[176:179], v[32:35]
	v_mfma_f32_16x16x32_bf16 v[32:35], v[164:167], v[180:183], v[32:35]
	v_mfma_f32_16x16x32_bf16 v[64:67], v[164:167], v[172:175], v[64:67]
	v_mfma_f32_16x16x32_bf16 v[64:67], v[160:163], v[168:171], v[64:67]
	s_setprio 0
	s_barrier
	s_add_i32 s83, s83, 2
	s_add_u32 s81, s81, 0x10000
	s_addc_u32 s82, s82, 0
	s_cmp_gt_u32 s83, 61
	s_mov_b64 s[52:53], s[2:3]
	s_cbranch_scc0 .LBB0_1539
	s_and_b64 vcc, exec, s[8:9]
	s_cbranch_vccz .LBB0_1542
	s_barrier

.LBB0_1675:
	ds_read_b128 v[48:51], v214
	ds_read_b128 v[64:67], v214 offset:1024
	ds_read_b128 v[80:83], v214 offset:2048
	ds_read_b128 v[92:95], v214 offset:3072
	ds_read_b128 v[104:107], v215
	ds_read_b128 v[116:119], v215 offset:1024
	ds_read_b128 v[140:143], v215 offset:2048
	ds_read_b128 v[144:147], v215 offset:3072
	s_cmp_eq_u32 s93, 4
	s_cselect_b32 s2, s89, s54
	s_cselect_b32 s3, s43, s55
	s_cselect_b32 s60, s90, s91
	s_cselect_b32 s61, s41, s92
	s_add_u32 s58, s2, 0x8000
	s_addc_u32 s59, s3, 0
	ds_read_b128 v[156:159], v216
	ds_read_b128 v[168:171], v216 offset:1024
	ds_read_b128 v[172:175], v216 offset:2048
	ds_read_b128 v[176:179], v216 offset:3072
	ds_read_b128 v[180:183], v216 offset:4096
	ds_read_b128 v[184:187], v216 offset:5120
	ds_read_b128 v[188:191], v216 offset:6144
	ds_read_b128 v[194:197], v216 offset:7168
	s_add_u32 s52, s54, 0xffffc000
	s_addc_u32 s53, s55, -1
	s_mov_b32 m0, s77
	s_nop 0
	global_load_lds_dwordx4 v212, s[52:53]
	s_add_u32 s52, s54, 0xffffe000
	s_addc_u32 s53, s55, -1
	s_mov_b32 m0, s81
	s_nop 0
	global_load_lds_dwordx4 v212, s[52:53]
	s_waitcnt vmcnt(8)
	s_waitcnt lgkmcnt(0)
	s_add_u32 s52, s60, 0x8000
	s_addc_u32 s53, s61, 0
	s_barrier
	s_setprio 1
	s_waitcnt lgkmcnt(7)
	v_mfma_f32_16x16x32_bf16 v[164:167], v[48:51], v[156:159], v[164:167]
	v_mfma_f32_16x16x32_bf16 v[160:163], v[80:83], v[156:159], v[160:163]
	s_waitcnt lgkmcnt(5)
	v_mfma_f32_16x16x32_bf16 v[136:139], v[48:51], v[172:175], v[136:139]
	v_mfma_f32_16x16x32_bf16 v[130:133], v[80:83], v[172:175], v[132:135]
	s_waitcnt lgkmcnt(3)
	v_mfma_f32_16x16x32_bf16 v[112:115], v[48:51], v[180:183], v[112:115]
	v_mfma_f32_16x16x32_bf16 v[108:111], v[80:83], v[180:183], v[108:111]
	s_waitcnt lgkmcnt(1)
	v_mfma_f32_16x16x32_bf16 v[88:91], v[48:51], v[188:191], v[88:91]
	v_mfma_f32_16x16x32_bf16 v[84:87], v[80:83], v[188:191], v[84:87]
	v_mfma_f32_16x16x32_bf16 v[164:167], v[64:67], v[168:171], v[164:167]
	v_mfma_f32_16x16x32_bf16 v[160:163], v[92:95], v[168:171], v[160:163]
	v_mfma_f32_16x16x32_bf16 v[136:139], v[64:67], v[176:179], v[136:139]
	v_mfma_f32_16x16x32_bf16 v[130:133], v[92:95], v[176:179], v[130:133]
	v_mfma_f32_16x16x32_bf16 v[112:115], v[64:67], v[184:187], v[112:115]
	v_mfma_f32_16x16x32_bf16 v[108:111], v[92:95], v[184:187], v[108:111]
	s_waitcnt lgkmcnt(0)
	v_mfma_f32_16x16x32_bf16 v[88:91], v[64:67], v[194:197], v[88:91]
	v_mfma_f32_16x16x32_bf16 v[84:87], v[92:95], v[194:197], v[84:87]
	s_setprio 0
	s_setprio 1
	s_waitcnt lgkmcnt(0)
	v_mfma_f32_16x16x32_bf16 v[152:155], v[104:107], v[156:159], v[152:155]
	v_mfma_f32_16x16x32_bf16 v[152:155], v[116:119], v[168:171], v[152:155]
	v_mfma_f32_16x16x32_bf16 v[124:127], v[116:119], v[176:179], v[124:127]
	v_mfma_f32_16x16x32_bf16 v[124:127], v[104:107], v[172:175], v[124:127]
	v_mfma_f32_16x16x32_bf16 v[100:103], v[104:107], v[180:183], v[100:103]
	v_mfma_f32_16x16x32_bf16 v[100:103], v[116:119], v[184:187], v[100:103]
	v_mfma_f32_16x16x32_bf16 v[76:79], v[116:119], v[194:197], v[76:79]
	v_mfma_f32_16x16x32_bf16 v[76:79], v[104:107], v[188:191], v[76:79]
	v_mfma_f32_16x16x32_bf16 v[72:75], v[140:143], v[188:191], v[72:75]
	v_mfma_f32_16x16x32_bf16 v[72:75], v[144:147], v[194:197], v[72:75]
	v_mfma_f32_16x16x32_bf16 v[96:99], v[144:147], v[184:187], v[96:99]
	v_mfma_f32_16x16x32_bf16 v[96:99], v[140:143], v[180:183], v[96:99]
	v_mfma_f32_16x16x32_bf16 v[120:123], v[140:143], v[172:175], v[120:123]
	v_mfma_f32_16x16x32_bf16 v[120:123], v[144:147], v[176:179], v[120:123]
	v_mfma_f32_16x16x32_bf16 v[148:151], v[144:147], v[168:171], v[148:151]
	v_mfma_f32_16x16x32_bf16 v[148:151], v[140:143], v[156:159], v[148:151]
	s_setprio 0
	s_barrier
	s_add_u32 s96, s60, 0x2000
	ds_read_b128 v[156:159], v216 offset:16384
	ds_read_b128 v[168:171], v216 offset:17408
	ds_read_b128 v[172:175], v216 offset:18432
	ds_read_b128 v[176:179], v216 offset:19456
	ds_read_b128 v[180:183], v216 offset:20480
	ds_read_b128 v[184:187], v216 offset:21504
	ds_read_b128 v[188:191], v216 offset:22528
	ds_read_b128 v[194:197], v216 offset:23552
	s_mov_b32 m0, s49
	s_nop 0
	global_load_lds_dwordx4 v212, s[60:61]
	s_addc_u32 s97, s61, 0
	s_mov_b32 m0, s57
	s_nop 0
	global_load_lds_dwordx4 v212, s[96:97]
	s_add_u32 s96, s60, 0x4000
	s_addc_u32 s97, s61, 0
	s_mov_b32 m0, s63
	s_nop 0
	global_load_lds_dwordx4 v212, s[96:97]
	s_add_u32 s96, s60, 0x6000
	s_addc_u32 s97, s61, 0
	s_mov_b32 m0, s64
	s_nop 0
	global_load_lds_dwordx4 v212, s[96:97]
	s_add_u32 s96, s2, 0x2000
	s_mov_b32 m0, s62
	s_nop 0
	global_load_lds_dwordx4 v212, s[2:3]
	s_addc_u32 s97, s3, 0
	s_mov_b32 m0, s65
	s_nop 0
	global_load_lds_dwordx4 v212, s[96:97]
	s_waitcnt vmcnt(8)
	s_waitcnt lgkmcnt(0)
	s_barrier
	s_setprio 1
	s_waitcnt lgkmcnt(7)
	s_waitcnt lgkmcnt(0)
	v_mfma_f32_16x16x32_bf16 v[68:71], v[48:51], v[156:159], v[68:71]
	v_mfma_f32_16x16x32_bf16 v[68:71], v[64:67], v[168:171], v[68:71]
	v_mfma_f32_16x16x32_bf16 v[44:47], v[64:67], v[176:179], v[44:47]
	v_mfma_f32_16x16x32_bf16 v[44:47], v[48:51], v[172:175], v[44:47]
	v_mfma_f32_16x16x32_bf16 v[28:31], v[48:51], v[180:183], v[28:31]
	v_mfma_f32_16x16x32_bf16 v[28:31], v[64:67], v[184:187], v[28:31]
	v_mfma_f32_16x16x32_bf16 v[12:15], v[64:67], v[194:197], v[12:15]
	v_mfma_f32_16x16x32_bf16 v[12:15], v[48:51], v[188:191], v[12:15]
	v_mfma_f32_16x16x32_bf16 v[8:11], v[80:83], v[188:191], v[8:11]
	v_mfma_f32_16x16x32_bf16 v[8:11], v[92:95], v[194:197], v[8:11]
	v_mfma_f32_16x16x32_bf16 v[24:27], v[92:95], v[184:187], v[24:27]
	v_mfma_f32_16x16x32_bf16 v[24:27], v[80:83], v[180:183], v[24:27]
	v_mfma_f32_16x16x32_bf16 v[40:43], v[80:83], v[172:175], v[40:43]
	v_mfma_f32_16x16x32_bf16 v[40:43], v[92:95], v[176:179], v[40:43]
	v_mfma_f32_16x16x32_bf16 v[60:63], v[92:95], v[168:171], v[60:63]
	v_mfma_f32_16x16x32_bf16 v[60:63], v[80:83], v[156:159], v[60:63]
	s_setprio 0
	s_setprio 1
	v_mfma_f32_16x16x32_bf16 v[52:55], v[140:143], v[156:159], v[52:55]
	v_mfma_f32_16x16x32_bf16 v[36:39], v[104:107], v[172:175], v[36:39]
	v_mfma_f32_16x16x32_bf16 v[32:35], v[140:143], v[172:175], v[32:35]
	v_mfma_f32_16x16x32_bf16 v[20:23], v[104:107], v[180:183], v[20:23]
	v_mfma_f32_16x16x32_bf16 v[16:19], v[140:143], v[180:183], v[16:19]
	v_mfma_f32_16x16x32_bf16 v[4:7], v[104:107], v[188:191], v[4:7]
	v_mfma_f32_16x16x32_bf16 v[0:3], v[140:143], v[188:191], v[0:3]
	v_mfma_f32_16x16x32_bf16 v[48:51], v[104:107], v[156:159], v[56:59]
	v_mfma_f32_16x16x32_bf16 v[52:55], v[144:147], v[168:171], v[52:55]
	v_mfma_f32_16x16x32_bf16 v[36:39], v[116:119], v[176:179], v[36:39]
	v_mfma_f32_16x16x32_bf16 v[32:35], v[144:147], v[176:179], v[32:35]
	v_mfma_f32_16x16x32_bf16 v[20:23], v[116:119], v[184:187], v[20:23]
	v_mfma_f32_16x16x32_bf16 v[16:19], v[144:147], v[184:187], v[16:19]
	v_mfma_f32_16x16x32_bf16 v[4:7], v[116:119], v[194:197], v[4:7]
	v_mfma_f32_16x16x32_bf16 v[0:3], v[144:147], v[194:197], v[0:3]
	v_mfma_f32_16x16x32_bf16 v[48:51], v[116:119], v[168:171], v[48:51]
	s_setprio 0
	s_barrier
	ds_read_b128 v[56:59], v128
	ds_read_b128 v[64:67], v128 offset:1024
	ds_read_b128 v[80:83], v128 offset:2048
	ds_read_b128 v[92:95], v128 offset:3072
	ds_read_b128 v[104:107], v129
	ds_read_b128 v[116:119], v129 offset:1024
	ds_read_b128 v[140:143], v129 offset:2048
	ds_read_b128 v[144:147], v129 offset:3072
	ds_read_b128 v[156:159], v216 offset:32768
	ds_read_b128 v[168:171], v216 offset:33792
	ds_read_b128 v[172:175], v216 offset:34816
	ds_read_b128 v[176:179], v216 offset:35840
	ds_read_b128 v[180:183], v216 offset:36864
	ds_read_b128 v[184:187], v216 offset:37888
	ds_read_b128 v[188:191], v216 offset:38912
	ds_read_b128 v[194:197], v216 offset:39936
	s_add_u32 s96, s2, 0x4000
	s_addc_u32 s97, s3, 0
	s_mov_b32 m0, s66
	s_nop 0
	global_load_lds_dwordx4 v212, s[96:97]
	s_add_u32 s96, s2, 0x6000
	s_addc_u32 s97, s3, 0
	s_mov_b32 m0, s67
	s_nop 0
	global_load_lds_dwordx4 v212, s[96:97]
	s_waitcnt vmcnt(8)
	s_waitcnt lgkmcnt(0)
	s_barrier
	s_setprio 1
	s_waitcnt lgkmcnt(7)
	v_mfma_f32_16x16x32_bf16 v[164:167], v[56:59], v[156:159], v[164:167]
	v_mfma_f32_16x16x32_bf16 v[160:163], v[80:83], v[156:159], v[160:163]
	s_waitcnt lgkmcnt(5)
	v_mfma_f32_16x16x32_bf16 v[134:137], v[56:59], v[172:175], v[136:139]
	v_mfma_f32_16x16x32_bf16 v[130:133], v[80:83], v[172:175], v[130:133]
	s_waitcnt lgkmcnt(3)
	v_mfma_f32_16x16x32_bf16 v[112:115], v[56:59], v[180:183], v[112:115]
	v_mfma_f32_16x16x32_bf16 v[108:111], v[80:83], v[180:183], v[108:111]
	s_waitcnt lgkmcnt(1)
	v_mfma_f32_16x16x32_bf16 v[88:91], v[56:59], v[188:191], v[88:91]
	v_mfma_f32_16x16x32_bf16 v[84:87], v[80:83], v[188:191], v[84:87]
	v_mfma_f32_16x16x32_bf16 v[164:167], v[64:67], v[168:171], v[164:167]
	v_mfma_f32_16x16x32_bf16 v[160:163], v[92:95], v[168:171], v[160:163]
	v_mfma_f32_16x16x32_bf16 v[136:139], v[64:67], v[176:179], v[134:137]
	v_mfma_f32_16x16x32_bf16 v[132:135], v[92:95], v[176:179], v[130:133]
	v_mfma_f32_16x16x32_bf16 v[112:115], v[64:67], v[184:187], v[112:115]
	v_mfma_f32_16x16x32_bf16 v[108:111], v[92:95], v[184:187], v[108:111]
	s_waitcnt lgkmcnt(0)
	v_mfma_f32_16x16x32_bf16 v[88:91], v[64:67], v[194:197], v[88:91]
	v_mfma_f32_16x16x32_bf16 v[84:87], v[92:95], v[194:197], v[84:87]
	s_setprio 0
	s_setprio 1
	s_waitcnt lgkmcnt(0)
	v_mfma_f32_16x16x32_bf16 v[152:155], v[104:107], v[156:159], v[152:155]
	v_mfma_f32_16x16x32_bf16 v[152:155], v[116:119], v[168:171], v[152:155]
	v_mfma_f32_16x16x32_bf16 v[124:127], v[116:119], v[176:179], v[124:127]
	v_mfma_f32_16x16x32_bf16 v[124:127], v[104:107], v[172:175], v[124:127]
	v_mfma_f32_16x16x32_bf16 v[100:103], v[104:107], v[180:183], v[100:103]
	v_mfma_f32_16x16x32_bf16 v[100:103], v[116:119], v[184:187], v[100:103]
	v_mfma_f32_16x16x32_bf16 v[76:79], v[116:119], v[194:197], v[76:79]
	v_mfma_f32_16x16x32_bf16 v[76:79], v[104:107], v[188:191], v[76:79]
	v_mfma_f32_16x16x32_bf16 v[72:75], v[140:143], v[188:191], v[72:75]
	v_mfma_f32_16x16x32_bf16 v[72:75], v[144:147], v[194:197], v[72:75]
	v_mfma_f32_16x16x32_bf16 v[96:99], v[144:147], v[184:187], v[96:99]
	v_mfma_f32_16x16x32_bf16 v[96:99], v[140:143], v[180:183], v[96:99]
	v_mfma_f32_16x16x32_bf16 v[120:123], v[140:143], v[172:175], v[120:123]
	v_mfma_f32_16x16x32_bf16 v[120:123], v[144:147], v[176:179], v[120:123]
	v_mfma_f32_16x16x32_bf16 v[148:151], v[144:147], v[168:171], v[148:151]
	v_mfma_f32_16x16x32_bf16 v[148:151], v[140:143], v[156:159], v[148:151]
	s_setprio 0
	s_barrier
	ds_read_b128 v[156:159], v216 offset:49152
	ds_read_b128 v[168:171], v216 offset:50176
	ds_read_b128 v[172:175], v216 offset:51200
	ds_read_b128 v[176:179], v216 offset:52224
	ds_read_b128 v[180:183], v216 offset:53248
	ds_read_b128 v[184:187], v216 offset:54272
	ds_read_b128 v[188:191], v216 offset:55296
	ds_read_b128 v[194:197], v216 offset:56320
	s_mov_b32 m0, s71
	s_nop 0
	global_load_lds_dwordx4 v212, s[52:53]
	s_add_u32 s52, s60, 0xa000
	s_addc_u32 s53, s61, 0
	s_mov_b32 m0, s72
	s_nop 0
	global_load_lds_dwordx4 v212, s[52:53]
	s_add_u32 s52, s60, 0xc000
	s_addc_u32 s53, s61, 0
	s_mov_b32 m0, s75
	s_nop 0
	global_load_lds_dwordx4 v212, s[52:53]
	s_add_u32 s52, s60, 0xe000
	s_addc_u32 s53, s61, 0
	s_mov_b32 m0, s76
	s_nop 0
	global_load_lds_dwordx4 v212, s[52:53]
	s_add_u32 s2, s2, 0xa000
	s_mov_b32 m0, s73
	s_nop 0
	global_load_lds_dwordx4 v212, s[58:59]
	s_addc_u32 s3, s3, 0
	s_mov_b32 m0, s74
	s_nop 0
	global_load_lds_dwordx4 v212, s[2:3]
	s_waitcnt vmcnt(8)
	s_waitcnt lgkmcnt(0)
	s_barrier
	s_setprio 1
	s_waitcnt lgkmcnt(7)
	s_waitcnt lgkmcnt(0)
	v_mfma_f32_16x16x32_bf16 v[68:71], v[56:59], v[156:159], v[68:71]
	v_mfma_f32_16x16x32_bf16 v[68:71], v[64:67], v[168:171], v[68:71]
	v_mfma_f32_16x16x32_bf16 v[44:47], v[64:67], v[176:179], v[44:47]
	v_mfma_f32_16x16x32_bf16 v[44:47], v[56:59], v[172:175], v[44:47]
	v_mfma_f32_16x16x32_bf16 v[28:31], v[56:59], v[180:183], v[28:31]
	v_mfma_f32_16x16x32_bf16 v[28:31], v[64:67], v[184:187], v[28:31]
	v_mfma_f32_16x16x32_bf16 v[12:15], v[64:67], v[194:197], v[12:15]
	v_mfma_f32_16x16x32_bf16 v[12:15], v[56:59], v[188:191], v[12:15]
	v_mfma_f32_16x16x32_bf16 v[8:11], v[80:83], v[188:191], v[8:11]
	v_mfma_f32_16x16x32_bf16 v[8:11], v[92:95], v[194:197], v[8:11]
	v_mfma_f32_16x16x32_bf16 v[24:27], v[92:95], v[184:187], v[24:27]
	v_mfma_f32_16x16x32_bf16 v[24:27], v[80:83], v[180:183], v[24:27]
	v_mfma_f32_16x16x32_bf16 v[40:43], v[80:83], v[172:175], v[40:43]
	v_mfma_f32_16x16x32_bf16 v[40:43], v[92:95], v[176:179], v[40:43]
	v_mfma_f32_16x16x32_bf16 v[60:63], v[92:95], v[168:171], v[60:63]
	v_mfma_f32_16x16x32_bf16 v[60:63], v[80:83], v[156:159], v[60:63]
	s_setprio 0
	s_setprio 1
	v_mfma_f32_16x16x32_bf16 v[48:51], v[104:107], v[156:159], v[48:51]
	v_mfma_f32_16x16x32_bf16 v[56:59], v[116:119], v[168:171], v[48:51]
	v_mfma_f32_16x16x32_bf16 v[48:51], v[140:143], v[156:159], v[52:55]
	v_mfma_f32_16x16x32_bf16 v[36:39], v[104:107], v[172:175], v[36:39]
	v_mfma_f32_16x16x32_bf16 v[32:35], v[140:143], v[172:175], v[32:35]
	v_mfma_f32_16x16x32_bf16 v[20:23], v[104:107], v[180:183], v[20:23]
	v_mfma_f32_16x16x32_bf16 v[16:19], v[140:143], v[180:183], v[16:19]
	v_mfma_f32_16x16x32_bf16 v[4:7], v[104:107], v[188:191], v[4:7]
	v_mfma_f32_16x16x32_bf16 v[0:3], v[140:143], v[188:191], v[0:3]
	v_mfma_f32_16x16x32_bf16 v[52:55], v[144:147], v[168:171], v[48:51]
	v_mfma_f32_16x16x32_bf16 v[36:39], v[116:119], v[176:179], v[36:39]
	v_mfma_f32_16x16x32_bf16 v[32:35], v[144:147], v[176:179], v[32:35]
	v_mfma_f32_16x16x32_bf16 v[20:23], v[116:119], v[184:187], v[20:23]
	v_mfma_f32_16x16x32_bf16 v[16:19], v[144:147], v[184:187], v[16:19]
	v_mfma_f32_16x16x32_bf16 v[4:7], v[116:119], v[194:197], v[4:7]
	v_mfma_f32_16x16x32_bf16 v[0:3], v[144:147], v[194:197], v[0:3]
	s_setprio 0
	s_barrier
	s_add_i32 s93, s93, 2
	s_add_u32 s54, s54, 0x10000
	s_addc_u32 s55, s55, 0
	s_add_u32 s91, s91, 0x10000
	s_addc_u32 s92, s92, 0
	s_cmp_gt_u32 s93, 5
	s_cbranch_scc0 .LBB0_1675
	s_and_b64 vcc, exec, s[14:15]
	s_cbranch_vccz .LBB0_1678
	s_barrier

.LBB0_1953:
	ds_read_b128 v[134:137], v128
	ds_read_b128 v[138:141], v128 offset:1024
	ds_read_b128 v[142:145], v128 offset:2048
	ds_read_b128 v[146:149], v128 offset:3072
	ds_read_b128 v[150:153], v129
	ds_read_b128 v[154:157], v129 offset:1024
	ds_read_b128 v[158:161], v129 offset:2048
	ds_read_b128 v[162:165], v129 offset:3072
	s_add_u32 s2, s28, 0x10000
	s_addc_u32 s3, s29, 0
	s_cmp_eq_u32 s77, 8
	s_cselect_b32 s38, s26, s2
	s_cselect_b32 s39, s27, s3
	s_cselect_b32 s42, s23, s75
	s_cselect_b32 s43, s25, s76
	s_add_u32 s40, s38, 0x8000
	s_addc_u32 s41, s39, 0
	ds_read_b128 v[166:169], v130
	ds_read_b128 v[170:173], v130 offset:1024
	ds_read_b128 v[174:177], v130 offset:2048
	ds_read_b128 v[178:181], v130 offset:3072
	ds_read_b128 v[182:185], v130 offset:4096
	ds_read_b128 v[192:195], v130 offset:5120
	ds_read_b128 v[196:199], v130 offset:6144
	ds_read_b128 v[200:203], v130 offset:7168
	s_add_u32 s78, s28, 0xc000
	s_addc_u32 s79, s29, 0
	s_mov_b32 m0, s63
	s_nop 0
	global_load_lds_dwordx4 v210, s[78:79]
	s_add_u32 s28, s28, 0xe000
	s_addc_u32 s29, s29, 0
	s_mov_b32 m0, s66
	s_nop 0
	global_load_lds_dwordx4 v210, s[28:29]
	s_waitcnt vmcnt(8)
	s_waitcnt lgkmcnt(0)
	s_barrier
	s_setprio 1
	s_waitcnt lgkmcnt(7)
	s_waitcnt lgkmcnt(0)
	v_mfma_f32_16x16x32_bf16 v[124:127], v[134:137], v[166:169], v[124:127]
	v_mfma_f32_16x16x32_bf16 v[124:127], v[138:141], v[170:173], v[124:127]
	v_mfma_f32_16x16x32_bf16 v[108:111], v[138:141], v[178:181], v[108:111]
	v_mfma_f32_16x16x32_bf16 v[108:111], v[134:137], v[174:177], v[108:111]
	v_mfma_f32_16x16x32_bf16 v[92:95], v[134:137], v[182:185], v[92:95]
	v_mfma_f32_16x16x32_bf16 v[92:95], v[138:141], v[192:195], v[92:95]
	v_mfma_f32_16x16x32_bf16 v[76:79], v[138:141], v[200:203], v[76:79]
	v_mfma_f32_16x16x32_bf16 v[76:79], v[134:137], v[196:199], v[76:79]
	v_mfma_f32_16x16x32_bf16 v[72:75], v[142:145], v[196:199], v[72:75]
	v_mfma_f32_16x16x32_bf16 v[72:75], v[146:149], v[200:203], v[72:75]
	v_mfma_f32_16x16x32_bf16 v[88:91], v[146:149], v[192:195], v[88:91]
	v_mfma_f32_16x16x32_bf16 v[88:91], v[142:145], v[182:185], v[88:91]
	v_mfma_f32_16x16x32_bf16 v[104:107], v[142:145], v[174:177], v[104:107]
	v_mfma_f32_16x16x32_bf16 v[104:107], v[146:149], v[178:181], v[104:107]
	v_mfma_f32_16x16x32_bf16 v[120:123], v[146:149], v[170:173], v[120:123]
	v_mfma_f32_16x16x32_bf16 v[120:123], v[142:145], v[166:169], v[120:123]
	s_setprio 0
	s_setprio 1
	s_waitcnt lgkmcnt(0)
	v_mfma_f32_16x16x32_bf16 v[116:119], v[150:153], v[166:169], v[116:119]
	v_mfma_f32_16x16x32_bf16 v[116:119], v[154:157], v[170:173], v[116:119]
	v_mfma_f32_16x16x32_bf16 v[100:103], v[154:157], v[178:181], v[100:103]
	v_mfma_f32_16x16x32_bf16 v[100:103], v[150:153], v[174:177], v[100:103]
	v_mfma_f32_16x16x32_bf16 v[84:87], v[150:153], v[182:185], v[84:87]
	v_mfma_f32_16x16x32_bf16 v[84:87], v[154:157], v[192:195], v[84:87]
	v_mfma_f32_16x16x32_bf16 v[68:71], v[154:157], v[200:203], v[68:71]
	v_mfma_f32_16x16x32_bf16 v[68:71], v[150:153], v[196:199], v[68:71]
	v_mfma_f32_16x16x32_bf16 v[64:67], v[158:161], v[196:199], v[64:67]
	v_mfma_f32_16x16x32_bf16 v[64:67], v[162:165], v[200:203], v[64:67]
	v_mfma_f32_16x16x32_bf16 v[80:83], v[162:165], v[192:195], v[80:83]
	v_mfma_f32_16x16x32_bf16 v[80:83], v[158:161], v[182:185], v[80:83]
	v_mfma_f32_16x16x32_bf16 v[96:99], v[158:161], v[174:177], v[96:99]
	v_mfma_f32_16x16x32_bf16 v[96:99], v[162:165], v[178:181], v[96:99]
	v_mfma_f32_16x16x32_bf16 v[112:115], v[162:165], v[170:173], v[112:115]
	v_mfma_f32_16x16x32_bf16 v[112:115], v[158:161], v[166:169], v[112:115]
	s_setprio 0
	s_barrier
	s_add_u32 s28, s42, 0x2000
	ds_read_b128 v[166:169], v130 offset:16384
	ds_read_b128 v[170:173], v130 offset:17408
	ds_read_b128 v[174:177], v130 offset:18432
	ds_read_b128 v[178:181], v130 offset:19456
	ds_read_b128 v[182:185], v130 offset:20480
	ds_read_b128 v[192:195], v130 offset:21504
	ds_read_b128 v[196:199], v130 offset:22528
	ds_read_b128 v[200:203], v130 offset:23552
	s_mov_b32 m0, s46
	s_nop 0
	global_load_lds_dwordx4 v210, s[42:43]
	s_addc_u32 s29, s43, 0
	s_mov_b32 m0, s47
	s_nop 0
	global_load_lds_dwordx4 v210, s[28:29]
	s_add_u32 s28, s42, 0x4000
	s_addc_u32 s29, s43, 0
	s_mov_b32 m0, s48
	s_nop 0
	global_load_lds_dwordx4 v210, s[28:29]
	s_add_u32 s28, s42, 0x6000
	s_addc_u32 s29, s43, 0
	s_mov_b32 m0, s49
	s_nop 0
	global_load_lds_dwordx4 v210, s[28:29]
	s_add_u32 s28, s38, 0x2000
	s_mov_b32 m0, s45
	s_nop 0
	global_load_lds_dwordx4 v210, s[38:39]
	s_addc_u32 s29, s39, 0
	s_mov_b32 m0, s50
	s_nop 0
	global_load_lds_dwordx4 v210, s[28:29]
	s_waitcnt vmcnt(8)
	s_waitcnt lgkmcnt(0)
	s_barrier
	s_setprio 1
	s_waitcnt lgkmcnt(7)
	s_waitcnt lgkmcnt(0)
	v_mfma_f32_16x16x32_bf16 v[60:63], v[134:137], v[166:169], v[60:63]
	v_mfma_f32_16x16x32_bf16 v[60:63], v[138:141], v[170:173], v[60:63]
	v_mfma_f32_16x16x32_bf16 v[44:47], v[138:141], v[178:181], v[44:47]
	v_mfma_f32_16x16x32_bf16 v[44:47], v[134:137], v[174:177], v[44:47]
	v_mfma_f32_16x16x32_bf16 v[28:31], v[134:137], v[182:185], v[28:31]
	v_mfma_f32_16x16x32_bf16 v[28:31], v[138:141], v[192:195], v[28:31]
	v_mfma_f32_16x16x32_bf16 v[12:15], v[138:141], v[200:203], v[12:15]
	v_mfma_f32_16x16x32_bf16 v[12:15], v[134:137], v[196:199], v[12:15]
	v_mfma_f32_16x16x32_bf16 v[8:11], v[142:145], v[196:199], v[8:11]
	v_mfma_f32_16x16x32_bf16 v[8:11], v[146:149], v[200:203], v[8:11]
	v_mfma_f32_16x16x32_bf16 v[24:27], v[146:149], v[192:195], v[24:27]
	v_mfma_f32_16x16x32_bf16 v[24:27], v[142:145], v[182:185], v[24:27]
	v_mfma_f32_16x16x32_bf16 v[40:43], v[142:145], v[174:177], v[40:43]
	v_mfma_f32_16x16x32_bf16 v[40:43], v[146:149], v[178:181], v[40:43]
	v_mfma_f32_16x16x32_bf16 v[56:59], v[146:149], v[170:173], v[56:59]
	v_mfma_f32_16x16x32_bf16 v[56:59], v[142:145], v[166:169], v[56:59]
	s_setprio 0
	s_setprio 1
	s_waitcnt lgkmcnt(0)
	v_mfma_f32_16x16x32_bf16 v[52:55], v[150:153], v[166:169], v[52:55]
	v_mfma_f32_16x16x32_bf16 v[52:55], v[154:157], v[170:173], v[52:55]
	v_mfma_f32_16x16x32_bf16 v[36:39], v[154:157], v[178:181], v[36:39]
	v_mfma_f32_16x16x32_bf16 v[36:39], v[150:153], v[174:177], v[36:39]
	v_mfma_f32_16x16x32_bf16 v[20:23], v[150:153], v[182:185], v[20:23]
	v_mfma_f32_16x16x32_bf16 v[20:23], v[154:157], v[192:195], v[20:23]
	v_mfma_f32_16x16x32_bf16 v[4:7], v[154:157], v[200:203], v[4:7]
	v_mfma_f32_16x16x32_bf16 v[4:7], v[150:153], v[196:199], v[4:7]
	v_mfma_f32_16x16x32_bf16 v[0:3], v[158:161], v[196:199], v[0:3]
	v_mfma_f32_16x16x32_bf16 v[0:3], v[162:165], v[200:203], v[0:3]
	v_mfma_f32_16x16x32_bf16 v[16:19], v[162:165], v[192:195], v[16:19]
	v_mfma_f32_16x16x32_bf16 v[16:19], v[158:161], v[182:185], v[16:19]
	v_mfma_f32_16x16x32_bf16 v[32:35], v[158:161], v[174:177], v[32:35]
	v_mfma_f32_16x16x32_bf16 v[32:35], v[162:165], v[178:181], v[32:35]
	v_mfma_f32_16x16x32_bf16 v[48:51], v[162:165], v[170:173], v[48:51]
	v_mfma_f32_16x16x32_bf16 v[48:51], v[158:161], v[166:169], v[48:51]
	s_setprio 0
	s_barrier
	ds_read_b128 v[134:137], v131
	ds_read_b128 v[138:141], v131 offset:1024
	ds_read_b128 v[142:145], v131 offset:2048
	ds_read_b128 v[146:149], v131 offset:3072
	ds_read_b128 v[150:153], v132
	ds_read_b128 v[154:157], v132 offset:1024
	ds_read_b128 v[158:161], v132 offset:2048
	ds_read_b128 v[162:165], v132 offset:3072
	ds_read_b128 v[166:169], v130 offset:32768
	ds_read_b128 v[170:173], v130 offset:33792
	ds_read_b128 v[174:177], v130 offset:34816
	ds_read_b128 v[178:181], v130 offset:35840
	ds_read_b128 v[182:185], v130 offset:36864
	ds_read_b128 v[192:195], v130 offset:37888
	ds_read_b128 v[196:199], v130 offset:38912
	ds_read_b128 v[200:203], v130 offset:39936
	s_add_u32 s28, s38, 0x4000
	s_addc_u32 s29, s39, 0
	s_mov_b32 m0, s51
	s_nop 0
	global_load_lds_dwordx4 v210, s[28:29]
	s_add_u32 s28, s38, 0x6000
	s_addc_u32 s29, s39, 0
	s_mov_b32 m0, s52
	s_nop 0
	global_load_lds_dwordx4 v210, s[28:29]
	s_waitcnt vmcnt(8)
	s_waitcnt lgkmcnt(0)
	s_barrier
	s_setprio 1
	s_waitcnt lgkmcnt(7)
	s_waitcnt lgkmcnt(0)
	v_mfma_f32_16x16x32_bf16 v[124:127], v[134:137], v[166:169], v[124:127]
	v_mfma_f32_16x16x32_bf16 v[124:127], v[138:141], v[170:173], v[124:127]
	v_mfma_f32_16x16x32_bf16 v[108:111], v[138:141], v[178:181], v[108:111]
	v_mfma_f32_16x16x32_bf16 v[108:111], v[134:137], v[174:177], v[108:111]
	v_mfma_f32_16x16x32_bf16 v[92:95], v[134:137], v[182:185], v[92:95]
	v_mfma_f32_16x16x32_bf16 v[92:95], v[138:141], v[192:195], v[92:95]
	v_mfma_f32_16x16x32_bf16 v[76:79], v[138:141], v[200:203], v[76:79]
	v_mfma_f32_16x16x32_bf16 v[76:79], v[134:137], v[196:199], v[76:79]
	v_mfma_f32_16x16x32_bf16 v[72:75], v[142:145], v[196:199], v[72:75]
	v_mfma_f32_16x16x32_bf16 v[72:75], v[146:149], v[200:203], v[72:75]
	v_mfma_f32_16x16x32_bf16 v[88:91], v[146:149], v[192:195], v[88:91]
	v_mfma_f32_16x16x32_bf16 v[88:91], v[142:145], v[182:185], v[88:91]
	v_mfma_f32_16x16x32_bf16 v[104:107], v[142:145], v[174:177], v[104:107]
	v_mfma_f32_16x16x32_bf16 v[104:107], v[146:149], v[178:181], v[104:107]
	v_mfma_f32_16x16x32_bf16 v[120:123], v[146:149], v[170:173], v[120:123]
	v_mfma_f32_16x16x32_bf16 v[120:123], v[142:145], v[166:169], v[120:123]
	s_setprio 0
	s_setprio 1
	s_waitcnt lgkmcnt(0)
	v_mfma_f32_16x16x32_bf16 v[116:119], v[150:153], v[166:169], v[116:119]
	v_mfma_f32_16x16x32_bf16 v[116:119], v[154:157], v[170:173], v[116:119]
	v_mfma_f32_16x16x32_bf16 v[100:103], v[154:157], v[178:181], v[100:103]
	v_mfma_f32_16x16x32_bf16 v[100:103], v[150:153], v[174:177], v[100:103]
	v_mfma_f32_16x16x32_bf16 v[84:87], v[150:153], v[182:185], v[84:87]
	v_mfma_f32_16x16x32_bf16 v[84:87], v[154:157], v[192:195], v[84:87]
	v_mfma_f32_16x16x32_bf16 v[68:71], v[154:157], v[200:203], v[68:71]
	v_mfma_f32_16x16x32_bf16 v[68:71], v[150:153], v[196:199], v[68:71]
	v_mfma_f32_16x16x32_bf16 v[64:67], v[158:161], v[196:199], v[64:67]
	v_mfma_f32_16x16x32_bf16 v[64:67], v[162:165], v[200:203], v[64:67]
	v_mfma_f32_16x16x32_bf16 v[80:83], v[162:165], v[192:195], v[80:83]
	v_mfma_f32_16x16x32_bf16 v[80:83], v[158:161], v[182:185], v[80:83]
	v_mfma_f32_16x16x32_bf16 v[96:99], v[158:161], v[174:177], v[96:99]
	v_mfma_f32_16x16x32_bf16 v[96:99], v[162:165], v[178:181], v[96:99]
	v_mfma_f32_16x16x32_bf16 v[112:115], v[162:165], v[170:173], v[112:115]
	v_mfma_f32_16x16x32_bf16 v[112:115], v[158:161], v[166:169], v[112:115]
	s_setprio 0
	s_barrier
	s_add_u32 s28, s42, 0x8000
	s_addc_u32 s29, s43, 0
	ds_read_b128 v[166:169], v130 offset:49152
	ds_read_b128 v[170:173], v130 offset:50176
	ds_read_b128 v[174:177], v130 offset:51200
	ds_read_b128 v[178:181], v130 offset:52224
	ds_read_b128 v[182:185], v130 offset:53248
	ds_read_b128 v[192:195], v130 offset:54272
	ds_read_b128 v[196:199], v130 offset:55296
	ds_read_b128 v[200:203], v130 offset:56320
	s_mov_b32 m0, s53
	s_nop 0
	global_load_lds_dwordx4 v210, s[28:29]
	s_add_u32 s28, s42, 0xa000
	s_addc_u32 s29, s43, 0
	s_mov_b32 m0, s54
	s_nop 0
	global_load_lds_dwordx4 v210, s[28:29]
	s_add_u32 s28, s42, 0xc000
	s_addc_u32 s29, s43, 0
	s_mov_b32 m0, s57
	s_nop 0
	global_load_lds_dwordx4 v210, s[28:29]
	s_add_u32 s28, s42, 0xe000
	s_addc_u32 s29, s43, 0
	s_mov_b32 m0, s58
	s_nop 0
	global_load_lds_dwordx4 v210, s[28:29]
	s_add_u32 s28, s38, 0xa000
	s_mov_b32 m0, s55
	s_nop 0
	global_load_lds_dwordx4 v210, s[40:41]
	s_addc_u32 s29, s39, 0
	s_mov_b32 m0, s56
	s_nop 0
	global_load_lds_dwordx4 v210, s[28:29]
	s_waitcnt vmcnt(8)
	s_waitcnt lgkmcnt(0)
	s_barrier
	s_setprio 1
	s_waitcnt lgkmcnt(7)
	s_waitcnt lgkmcnt(0)
	v_mfma_f32_16x16x32_bf16 v[60:63], v[134:137], v[166:169], v[60:63]
	v_mfma_f32_16x16x32_bf16 v[60:63], v[138:141], v[170:173], v[60:63]
	v_mfma_f32_16x16x32_bf16 v[44:47], v[138:141], v[178:181], v[44:47]
	v_mfma_f32_16x16x32_bf16 v[44:47], v[134:137], v[174:177], v[44:47]
	v_mfma_f32_16x16x32_bf16 v[28:31], v[134:137], v[182:185], v[28:31]
	v_mfma_f32_16x16x32_bf16 v[28:31], v[138:141], v[192:195], v[28:31]
	v_mfma_f32_16x16x32_bf16 v[12:15], v[138:141], v[200:203], v[12:15]
	v_mfma_f32_16x16x32_bf16 v[12:15], v[134:137], v[196:199], v[12:15]
	v_mfma_f32_16x16x32_bf16 v[8:11], v[142:145], v[196:199], v[8:11]
	v_mfma_f32_16x16x32_bf16 v[8:11], v[146:149], v[200:203], v[8:11]
	v_mfma_f32_16x16x32_bf16 v[24:27], v[146:149], v[192:195], v[24:27]
	v_mfma_f32_16x16x32_bf16 v[24:27], v[142:145], v[182:185], v[24:27]
	v_mfma_f32_16x16x32_bf16 v[40:43], v[142:145], v[174:177], v[40:43]
	v_mfma_f32_16x16x32_bf16 v[40:43], v[146:149], v[178:181], v[40:43]
	v_mfma_f32_16x16x32_bf16 v[56:59], v[146:149], v[170:173], v[56:59]
	v_mfma_f32_16x16x32_bf16 v[56:59], v[142:145], v[166:169], v[56:59]
	s_setprio 0
	s_setprio 1
	s_waitcnt lgkmcnt(0)
	v_mfma_f32_16x16x32_bf16 v[52:55], v[150:153], v[166:169], v[52:55]
	v_mfma_f32_16x16x32_bf16 v[52:55], v[154:157], v[170:173], v[52:55]
	v_mfma_f32_16x16x32_bf16 v[36:39], v[154:157], v[178:181], v[36:39]
	v_mfma_f32_16x16x32_bf16 v[36:39], v[150:153], v[174:177], v[36:39]
	v_mfma_f32_16x16x32_bf16 v[20:23], v[150:153], v[182:185], v[20:23]
	v_mfma_f32_16x16x32_bf16 v[20:23], v[154:157], v[192:195], v[20:23]
	v_mfma_f32_16x16x32_bf16 v[4:7], v[154:157], v[200:203], v[4:7]
	v_mfma_f32_16x16x32_bf16 v[4:7], v[150:153], v[196:199], v[4:7]
	v_mfma_f32_16x16x32_bf16 v[0:3], v[158:161], v[196:199], v[0:3]
	v_mfma_f32_16x16x32_bf16 v[0:3], v[162:165], v[200:203], v[0:3]
	v_mfma_f32_16x16x32_bf16 v[16:19], v[162:165], v[192:195], v[16:19]
	v_mfma_f32_16x16x32_bf16 v[16:19], v[158:161], v[182:185], v[16:19]
	v_mfma_f32_16x16x32_bf16 v[32:35], v[158:161], v[174:177], v[32:35]
	v_mfma_f32_16x16x32_bf16 v[32:35], v[162:165], v[178:181], v[32:35]
	v_mfma_f32_16x16x32_bf16 v[48:51], v[162:165], v[170:173], v[48:51]
	v_mfma_f32_16x16x32_bf16 v[48:51], v[158:161], v[166:169], v[48:51]
	s_setprio 0
	s_barrier
	s_add_i32 s77, s77, 2
	s_add_u32 s75, s75, 0x10000
	s_addc_u32 s76, s76, 0
	s_cmp_gt_u32 s77, 9
	s_mov_b64 s[28:29], s[2:3]
	s_cbranch_scc0 .LBB0_1953
	v_mbcnt_lo_u32_b32 v128, -1, 0
	v_mbcnt_hi_u32_b32 v128, -1, v128
	s_add_u32 s19, s69, s19
	v_lshlrev_b32_e32 v128, 4, v128
	v_add_u32_e32 v129, s60, v128
	v_add_u32_e32 v128, s62, v128
	s_addc_u32 s17, s70, s17
	s_mov_b32 s23, -2
	v_add_u32_e32 v128, 0, v128
	v_add_u32_e32 v129, 0, v129
